# adds nt hint on sample-attention paged f32 K/V loads and on the state_win to new_win_s copy (on top of nt cache_cmp stream)
# speedup vs baseline: 1.0083x; 1.0083x over previous
.LBB0_147:
	v_lshl_add_u64 v[34:35], v[26:27], 0, s[10:11]
	v_cmp_gt_i64_e64 s[0:1], s[24:25], v[34:35]
	v_readlane_b32 s36, v241, 18
	v_readlane_b32 s37, v241, 19
	v_cndmask_b32_e64 v3, v27, v35, s[0:1]
	v_cndmask_b32_e64 v2, v26, v34, s[0:1]
	v_ashrrev_i32_e32 v1, 31, v3
	v_mul_lo_u32 v8, v1, s33
	v_mad_u64_u32 v[6:7], s[4:5], v1, s60, 0
	v_mul_hi_u32 v32, v2, s60
	v_add3_u32 v7, v7, v8, v6
	v_mad_u64_u32 v[8:9], s[4:5], v3, s60, v[32:33]
	v_mov_b32_e32 v32, v9
	v_mov_b32_e32 v9, v33
	v_mad_u64_u32 v[8:9], s[4:5], v2, s33, v[8:9]
	v_mad_u64_u32 v[6:7], s[4:5], v2, -1, v[6:7]
	v_mov_b32_e32 v8, v9
	v_mov_b32_e32 v9, v33
	v_sub_u32_e32 v1, v7, v3
	v_lshl_add_u64 v[8:9], v[32:33], 0, v[8:9]
	v_sub_u32_e32 v7, v1, v2
	v_mad_u64_u32 v[8:9], s[4:5], v3, s33, v[8:9]
	v_lshl_add_u64 v[6:7], v[8:9], 0, v[6:7]
	v_mad_u64_u32 v[6:7], s[4:5], v2, 1, v[6:7]
	v_lshlrev_b64 v[4:5], 2, v[2:3]
	v_add_u32_e32 v7, v3, v7
	v_lshrrev_b64 v[8:9], 15, v[6:7]
	v_lshrrev_b32_e32 v32, 31, v7
	v_ashrrev_i32_e32 v1, 31, v5
	v_lshl_add_u64 v[6:7], v[8:9], 0, v[32:33]
	v_mul_lo_u32 v10, v1, s33
	v_mad_u64_u32 v[8:9], s[4:5], v1, s60, 0
	v_add3_u32 v9, v9, v10, v8
	v_mad_u64_u32 v[8:9], s[4:5], v4, -1, v[8:9]
	v_alignbit_b32 v1, v3, v2, 30
	v_sub_u32_e32 v2, v9, v1
	v_mul_hi_u32 v32, v4, s60
	v_sub_u32_e32 v9, v2, v4
	v_mad_u64_u32 v[2:3], s[4:5], v1, s60, v[32:33]
	v_mov_b32_e32 v32, v3
	v_mov_b32_e32 v3, v33
	v_mad_u64_u32 v[2:3], s[4:5], v4, s33, v[2:3]
	v_mov_b32_e32 v2, v3
	v_mov_b32_e32 v3, v33
	v_lshl_add_u64 v[2:3], v[32:33], 0, v[2:3]
	v_mad_u64_u32 v[2:3], s[4:5], v1, s33, v[2:3]
	v_lshl_add_u64 v[2:3], v[2:3], 0, v[8:9]
	v_mad_u64_u32 v[2:3], s[4:5], v4, 1, v[2:3]
	v_add_u32_e32 v3, v1, v3
	v_ashrrev_i64 v[8:9], 17, v[2:3]
	v_lshrrev_b32_e32 v32, 31, v3
	v_lshl_add_u64 v[2:3], v[8:9], 0, v[32:33]
	v_mad_u64_u32 v[8:9], s[4:5], v2, s61, 0
	v_mad_i32_i24 v1, v3, s61, v9
	v_sub_co_u32_e32 v2, vcc, v4, v8
	v_lshl_add_u64 v[36:37], s[34:35], 0, v[26:27]
	s_nop 0
	v_subb_co_u32_e32 v3, vcc, v5, v1, vcc
	v_lshlrev_b64 v[4:5], 20, v[6:7]
	v_lshl_add_u64 v[4:5], s[36:37], 0, v[4:5]
	v_cmp_gt_i64_e64 s[4:5], s[24:25], v[36:37]
	v_lshl_add_u64 v[2:3], v[2:3], 2, v[4:5]
	v_add_co_u32_e32 v2, vcc, s62, v2
	v_cndmask_b32_e64 v5, v27, v37, s[4:5]
	v_cndmask_b32_e64 v4, v26, v36, s[4:5]
	v_ashrrev_i32_e32 v1, 31, v5
	v_mul_lo_u32 v10, v1, s33
	v_mad_u64_u32 v[8:9], s[6:7], v1, s60, 0
	v_mul_hi_u32 v32, v4, s60
	v_add3_u32 v9, v9, v10, v8
	v_mad_u64_u32 v[10:11], s[6:7], v5, s60, v[32:33]
	v_mov_b32_e32 v32, v11
	v_mov_b32_e32 v11, v33
	v_mad_u64_u32 v[10:11], s[6:7], v4, s33, v[10:11]
	v_mad_u64_u32 v[8:9], s[6:7], v4, -1, v[8:9]
	v_mov_b32_e32 v10, v11
	v_mov_b32_e32 v11, v33
	v_sub_u32_e32 v1, v9, v5
	v_lshl_add_u64 v[10:11], v[32:33], 0, v[10:11]
	v_sub_u32_e32 v9, v1, v4
	v_mad_u64_u32 v[10:11], s[6:7], v5, s33, v[10:11]
	v_lshl_add_u64 v[8:9], v[10:11], 0, v[8:9]
	v_mad_u64_u32 v[8:9], s[6:7], v4, 1, v[8:9]
	v_lshlrev_b64 v[6:7], 2, v[4:5]
	v_add_u32_e32 v9, v5, v9
	v_lshrrev_b64 v[10:11], 15, v[8:9]
	v_lshrrev_b32_e32 v32, 31, v9
	v_ashrrev_i32_e32 v1, 31, v7
	v_lshl_add_u64 v[8:9], v[10:11], 0, v[32:33]
	v_mul_lo_u32 v12, v1, s33
	v_mad_u64_u32 v[10:11], s[6:7], v1, s60, 0
	v_add3_u32 v11, v11, v12, v10
	v_mad_u64_u32 v[10:11], s[6:7], v6, -1, v[10:11]
	v_alignbit_b32 v1, v5, v4, 30
	v_sub_u32_e32 v4, v11, v1
	v_mul_hi_u32 v32, v6, s60
	v_sub_u32_e32 v11, v4, v6
	v_mad_u64_u32 v[4:5], s[6:7], v1, s60, v[32:33]
	v_mov_b32_e32 v32, v5
	v_mov_b32_e32 v5, v33
	v_mad_u64_u32 v[4:5], s[6:7], v6, s33, v[4:5]
	v_mov_b32_e32 v4, v5
	v_mov_b32_e32 v5, v33
	v_lshl_add_u64 v[4:5], v[32:33], 0, v[4:5]
	v_mad_u64_u32 v[4:5], s[6:7], v1, s33, v[4:5]
	v_lshl_add_u64 v[4:5], v[4:5], 0, v[10:11]
	v_mad_u64_u32 v[4:5], s[6:7], v6, 1, v[4:5]
	v_add_u32_e32 v5, v1, v5
	v_ashrrev_i64 v[10:11], 17, v[4:5]
	v_lshrrev_b32_e32 v32, 31, v5
	v_lshl_add_u64 v[4:5], v[10:11], 0, v[32:33]
	v_addc_co_u32_e32 v3, vcc, 0, v3, vcc
	v_mad_u64_u32 v[10:11], s[6:7], v4, s61, 0
	v_mad_i32_i24 v1, v5, s61, v11
	v_sub_co_u32_e32 v4, vcc, v6, v10
	v_lshl_add_u64 v[38:39], s[72:73], 0, v[26:27]
	s_nop 0
	v_subb_co_u32_e32 v5, vcc, v7, v1, vcc
	v_lshlrev_b64 v[6:7], 20, v[8:9]
	v_lshl_add_u64 v[6:7], s[36:37], 0, v[6:7]
	v_cmp_gt_i64_e64 s[6:7], s[24:25], v[38:39]
	v_lshl_add_u64 v[4:5], v[4:5], 2, v[6:7]
	v_add_co_u32_e32 v4, vcc, s62, v4
	v_cndmask_b32_e64 v7, v27, v39, s[6:7]
	v_cndmask_b32_e64 v6, v26, v38, s[6:7]
	v_ashrrev_i32_e32 v1, 31, v7
	v_mul_lo_u32 v12, v1, s33
	v_mad_u64_u32 v[10:11], s[8:9], v1, s60, 0
	v_mul_hi_u32 v32, v6, s60
	v_add3_u32 v11, v11, v12, v10
	v_mad_u64_u32 v[12:13], s[8:9], v7, s60, v[32:33]
	v_mov_b32_e32 v32, v13
	v_mov_b32_e32 v13, v33
	v_mad_u64_u32 v[12:13], s[8:9], v6, s33, v[12:13]
	v_mad_u64_u32 v[10:11], s[8:9], v6, -1, v[10:11]
	v_mov_b32_e32 v12, v13
	v_mov_b32_e32 v13, v33
	v_sub_u32_e32 v1, v11, v7
	v_lshl_add_u64 v[12:13], v[32:33], 0, v[12:13]
	v_sub_u32_e32 v11, v1, v6
	v_mad_u64_u32 v[12:13], s[8:9], v7, s33, v[12:13]
	v_lshl_add_u64 v[10:11], v[12:13], 0, v[10:11]
	v_mad_u64_u32 v[10:11], s[8:9], v6, 1, v[10:11]
	v_lshlrev_b64 v[8:9], 2, v[6:7]
	v_add_u32_e32 v11, v7, v11
	v_lshrrev_b64 v[12:13], 15, v[10:11]
	v_lshrrev_b32_e32 v32, 31, v11
	v_ashrrev_i32_e32 v1, 31, v9
	v_lshl_add_u64 v[10:11], v[12:13], 0, v[32:33]
	v_mul_lo_u32 v18, v1, s33
	v_mad_u64_u32 v[12:13], s[8:9], v1, s60, 0
	v_add3_u32 v13, v13, v18, v12
	v_mad_u64_u32 v[12:13], s[8:9], v8, -1, v[12:13]
	v_alignbit_b32 v1, v7, v6, 30
	v_sub_u32_e32 v6, v13, v1
	v_mul_hi_u32 v32, v8, s60
	v_sub_u32_e32 v13, v6, v8
	v_mad_u64_u32 v[6:7], s[8:9], v1, s60, v[32:33]
	v_mov_b32_e32 v32, v7
	v_mov_b32_e32 v7, v33
	v_mad_u64_u32 v[6:7], s[8:9], v8, s33, v[6:7]
	v_mov_b32_e32 v6, v7
	v_mov_b32_e32 v7, v33
	v_lshl_add_u64 v[6:7], v[32:33], 0, v[6:7]
	v_mad_u64_u32 v[6:7], s[8:9], v1, s33, v[6:7]
	v_lshl_add_u64 v[6:7], v[6:7], 0, v[12:13]
	v_mad_u64_u32 v[6:7], s[8:9], v8, 1, v[6:7]
	v_add_u32_e32 v7, v1, v7
	v_ashrrev_i64 v[12:13], 17, v[6:7]
	v_lshrrev_b32_e32 v32, 31, v7
	v_lshl_add_u64 v[6:7], v[12:13], 0, v[32:33]
	v_addc_co_u32_e32 v5, vcc, 0, v5, vcc
	v_mad_u64_u32 v[12:13], s[8:9], v6, s61, 0
	v_mad_i32_i24 v1, v7, s61, v13
	v_sub_co_u32_e32 v6, vcc, v8, v12
	v_lshl_add_u64 v[40:41], s[54:55], 0, v[26:27]
	s_nop 0
	v_subb_co_u32_e32 v7, vcc, v9, v1, vcc
	v_lshlrev_b64 v[8:9], 20, v[10:11]
	v_lshl_add_u64 v[8:9], s[36:37], 0, v[8:9]
	v_cmp_gt_i64_e64 s[8:9], s[24:25], v[40:41]
	v_lshl_add_u64 v[6:7], v[6:7], 2, v[8:9]
	v_add_co_u32_e32 v6, vcc, s62, v6
	v_cndmask_b32_e64 v9, v27, v41, s[8:9]
	v_cndmask_b32_e64 v8, v26, v40, s[8:9]
	v_ashrrev_i32_e32 v1, 31, v9
	v_mul_lo_u32 v18, v1, s33
	v_mad_u64_u32 v[12:13], s[12:13], v1, s60, 0
	v_mul_hi_u32 v32, v8, s60
	v_add3_u32 v13, v13, v18, v12
	v_mad_u64_u32 v[18:19], s[12:13], v9, s60, v[32:33]
	v_mov_b32_e32 v32, v19
	v_mov_b32_e32 v19, v33
	v_mad_u64_u32 v[18:19], s[12:13], v8, s33, v[18:19]
	v_mad_u64_u32 v[12:13], s[12:13], v8, -1, v[12:13]
	v_mov_b32_e32 v18, v19
	v_mov_b32_e32 v19, v33
	v_sub_u32_e32 v1, v13, v9
	v_lshl_add_u64 v[18:19], v[32:33], 0, v[18:19]
	v_sub_u32_e32 v13, v1, v8
	v_mad_u64_u32 v[18:19], s[12:13], v9, s33, v[18:19]
	v_lshl_add_u64 v[12:13], v[18:19], 0, v[12:13]
	v_mad_u64_u32 v[12:13], s[12:13], v8, 1, v[12:13]
	v_lshlrev_b64 v[10:11], 2, v[8:9]
	v_add_u32_e32 v13, v9, v13
	v_lshrrev_b64 v[18:19], 15, v[12:13]
	v_lshrrev_b32_e32 v32, 31, v13
	v_ashrrev_i32_e32 v1, 31, v11
	v_lshl_add_u64 v[12:13], v[18:19], 0, v[32:33]
	v_mul_lo_u32 v20, v1, s33
	v_mad_u64_u32 v[18:19], s[12:13], v1, s60, 0
	v_add3_u32 v19, v19, v20, v18
	v_mad_u64_u32 v[18:19], s[12:13], v10, -1, v[18:19]
	v_alignbit_b32 v1, v9, v8, 30
	v_sub_u32_e32 v8, v19, v1
	v_mul_hi_u32 v32, v10, s60
	v_sub_u32_e32 v19, v8, v10
	v_mad_u64_u32 v[8:9], s[12:13], v1, s60, v[32:33]
	v_mov_b32_e32 v32, v9
	v_mov_b32_e32 v9, v33
	v_mad_u64_u32 v[8:9], s[12:13], v10, s33, v[8:9]
	v_mov_b32_e32 v8, v9
	v_mov_b32_e32 v9, v33
	v_lshl_add_u64 v[8:9], v[32:33], 0, v[8:9]
	v_mad_u64_u32 v[8:9], s[12:13], v1, s33, v[8:9]
	v_lshl_add_u64 v[8:9], v[8:9], 0, v[18:19]
	v_mad_u64_u32 v[8:9], s[12:13], v10, 1, v[8:9]
	v_add_u32_e32 v9, v1, v9
	v_ashrrev_i64 v[18:19], 17, v[8:9]
	v_lshrrev_b32_e32 v32, 31, v9
	v_lshl_add_u64 v[8:9], v[18:19], 0, v[32:33]
	v_addc_co_u32_e32 v7, vcc, 0, v7, vcc
	v_mad_u64_u32 v[18:19], s[12:13], v8, s61, 0
	v_mad_i32_i24 v1, v9, s61, v19
	v_sub_co_u32_e32 v8, vcc, v10, v18
	v_lshl_add_u64 v[42:43], s[58:59], 0, v[26:27]
	s_nop 0
	v_subb_co_u32_e32 v9, vcc, v11, v1, vcc
	v_lshlrev_b64 v[10:11], 20, v[12:13]
	v_lshl_add_u64 v[10:11], s[36:37], 0, v[10:11]
	v_cmp_gt_i64_e64 s[12:13], s[24:25], v[42:43]
	v_lshl_add_u64 v[8:9], v[8:9], 2, v[10:11]
	v_add_co_u32_e32 v8, vcc, s62, v8
	v_cndmask_b32_e64 v11, v27, v43, s[12:13]
	v_cndmask_b32_e64 v10, v26, v42, s[12:13]
	v_ashrrev_i32_e32 v1, 31, v11
	v_mul_lo_u32 v24, v1, s33
	v_mad_u64_u32 v[22:23], s[14:15], v1, s60, 0
	v_mul_hi_u32 v32, v10, s60
	v_add3_u32 v23, v23, v24, v22
	v_mad_u64_u32 v[24:25], s[14:15], v11, s60, v[32:33]
	v_mov_b32_e32 v32, v25
	v_mov_b32_e32 v25, v33
	v_mad_u64_u32 v[24:25], s[14:15], v10, s33, v[24:25]
	v_mad_u64_u32 v[22:23], s[14:15], v10, -1, v[22:23]
	v_mov_b32_e32 v24, v25
	v_mov_b32_e32 v25, v33
	v_sub_u32_e32 v1, v23, v11
	v_lshl_add_u64 v[24:25], v[32:33], 0, v[24:25]
	v_sub_u32_e32 v23, v1, v10
	v_mad_u64_u32 v[24:25], s[14:15], v11, s33, v[24:25]
	v_lshl_add_u64 v[22:23], v[24:25], 0, v[22:23]
	v_mad_u64_u32 v[22:23], s[14:15], v10, 1, v[22:23]
	v_lshlrev_b64 v[12:13], 2, v[10:11]
	v_add_u32_e32 v23, v11, v23
	v_lshrrev_b64 v[24:25], 15, v[22:23]
	v_lshrrev_b32_e32 v32, 31, v23
	v_ashrrev_i32_e32 v1, 31, v13
	v_lshl_add_u64 v[22:23], v[24:25], 0, v[32:33]
	v_mul_lo_u32 v28, v1, s33
	v_mad_u64_u32 v[24:25], s[14:15], v1, s60, 0
	v_add3_u32 v25, v25, v28, v24
	v_mad_u64_u32 v[24:25], s[14:15], v12, -1, v[24:25]
	v_alignbit_b32 v1, v11, v10, 30
	v_sub_u32_e32 v10, v25, v1
	v_mul_hi_u32 v32, v12, s60
	v_sub_u32_e32 v25, v10, v12
	v_mad_u64_u32 v[10:11], s[14:15], v1, s60, v[32:33]
	v_mov_b32_e32 v32, v11
	v_mov_b32_e32 v11, v33
	v_mad_u64_u32 v[10:11], s[14:15], v12, s33, v[10:11]
	v_mov_b32_e32 v10, v11
	v_mov_b32_e32 v11, v33
	v_lshl_add_u64 v[10:11], v[32:33], 0, v[10:11]
	v_mad_u64_u32 v[10:11], s[14:15], v1, s33, v[10:11]
	v_lshl_add_u64 v[10:11], v[10:11], 0, v[24:25]
	v_mad_u64_u32 v[10:11], s[14:15], v12, 1, v[10:11]
	v_add_u32_e32 v11, v1, v11
	v_ashrrev_i64 v[24:25], 17, v[10:11]
	v_lshrrev_b32_e32 v32, 31, v11
	v_lshl_add_u64 v[10:11], v[24:25], 0, v[32:33]
	v_addc_co_u32_e32 v9, vcc, 0, v9, vcc
	v_mad_u64_u32 v[24:25], s[14:15], v10, s61, 0
	v_mad_i32_i24 v1, v11, s61, v25
	v_sub_co_u32_e32 v10, vcc, v12, v24
	v_lshl_add_u64 v[44:45], s[66:67], 0, v[26:27]
	s_nop 0
	v_subb_co_u32_e32 v11, vcc, v13, v1, vcc
	v_lshlrev_b64 v[12:13], 20, v[22:23]
	v_lshl_add_u64 v[12:13], s[36:37], 0, v[12:13]
	v_cmp_gt_i64_e64 s[14:15], s[24:25], v[44:45]
	v_lshl_add_u64 v[10:11], v[10:11], 2, v[12:13]
	v_add_co_u32_e32 v10, vcc, s62, v10
	v_cndmask_b32_e64 v13, v27, v45, s[14:15]
	v_cndmask_b32_e64 v12, v26, v44, s[14:15]
	v_ashrrev_i32_e32 v1, 31, v13
	v_mul_lo_u32 v28, v1, s33
	v_mad_u64_u32 v[24:25], s[16:17], v1, s60, 0
	v_mul_hi_u32 v32, v12, s60
	v_add3_u32 v25, v25, v28, v24
	v_mad_u64_u32 v[28:29], s[16:17], v13, s60, v[32:33]
	v_mov_b32_e32 v32, v29
	v_mov_b32_e32 v29, v33
	v_mad_u64_u32 v[28:29], s[16:17], v12, s33, v[28:29]
	v_mad_u64_u32 v[24:25], s[16:17], v12, -1, v[24:25]
	v_mov_b32_e32 v28, v29
	v_mov_b32_e32 v29, v33
	v_sub_u32_e32 v1, v25, v13
	v_lshl_add_u64 v[28:29], v[32:33], 0, v[28:29]
	v_sub_u32_e32 v25, v1, v12
	v_mad_u64_u32 v[28:29], s[16:17], v13, s33, v[28:29]
	v_lshl_add_u64 v[24:25], v[28:29], 0, v[24:25]
	v_mad_u64_u32 v[24:25], s[16:17], v12, 1, v[24:25]
	v_lshlrev_b64 v[22:23], 2, v[12:13]
	v_add_u32_e32 v25, v13, v25
	v_lshrrev_b64 v[28:29], 15, v[24:25]
	v_lshrrev_b32_e32 v32, 31, v25
	v_ashrrev_i32_e32 v1, 31, v23
	v_lshl_add_u64 v[24:25], v[28:29], 0, v[32:33]
	v_mul_lo_u32 v32, v1, s33
	v_mad_u64_u32 v[28:29], s[16:17], v1, s60, 0
	v_add3_u32 v29, v29, v32, v28
	v_mad_u64_u32 v[28:29], s[16:17], v22, -1, v[28:29]
	v_alignbit_b32 v1, v13, v12, 30
	v_sub_u32_e32 v12, v29, v1
	v_mul_hi_u32 v32, v22, s60
	v_sub_u32_e32 v29, v12, v22
	v_mad_u64_u32 v[12:13], s[16:17], v1, s60, v[32:33]
	v_mov_b32_e32 v32, v13
	v_mov_b32_e32 v13, v33
	v_mad_u64_u32 v[12:13], s[16:17], v22, s33, v[12:13]
	v_mov_b32_e32 v12, v13
	v_mov_b32_e32 v13, v33
	v_lshl_add_u64 v[12:13], v[32:33], 0, v[12:13]
	v_mad_u64_u32 v[12:13], s[16:17], v1, s33, v[12:13]
	v_lshl_add_u64 v[12:13], v[12:13], 0, v[28:29]
	v_mad_u64_u32 v[12:13], s[16:17], v22, 1, v[12:13]
	v_add_u32_e32 v13, v1, v13
	v_ashrrev_i64 v[28:29], 17, v[12:13]
	v_lshrrev_b32_e32 v32, 31, v13
	v_lshl_add_u64 v[12:13], v[28:29], 0, v[32:33]
	v_mad_u64_u32 v[28:29], s[16:17], v12, s61, 0
	v_lshl_add_u64 v[46:47], s[78:79], 0, v[26:27]
	v_addc_co_u32_e32 v11, vcc, 0, v11, vcc
	v_cmp_gt_i64_e64 s[16:17], s[24:25], v[46:47]
	v_mad_i32_i24 v1, v13, s61, v29
	v_sub_co_u32_e32 v12, vcc, v22, v28
	v_cndmask_b32_e64 v29, v27, v47, s[16:17]
	s_nop 0
	v_subb_co_u32_e32 v13, vcc, v23, v1, vcc
	v_ashrrev_i32_e32 v1, 31, v29
	v_cndmask_b32_e64 v28, v26, v46, s[16:17]
	v_mul_lo_u32 v32, v1, s33
	v_mad_u64_u32 v[50:51], s[68:69], v1, s60, 0
	v_add3_u32 v51, v51, v32, v50
	v_mul_hi_u32 v32, v28, s60
	v_mad_u64_u32 v[52:53], s[68:69], v29, s60, v[32:33]
	v_mov_b32_e32 v32, v53
	v_mov_b32_e32 v53, v33
	v_mad_u64_u32 v[52:53], s[68:69], v28, s33, v[52:53]
	v_mad_u64_u32 v[50:51], s[68:69], v28, -1, v[50:51]
	v_mov_b32_e32 v52, v53
	v_mov_b32_e32 v53, v33
	v_sub_u32_e32 v1, v51, v29
	v_lshl_add_u64 v[52:53], v[32:33], 0, v[52:53]
	v_sub_u32_e32 v51, v1, v28
	v_mad_u64_u32 v[52:53], s[68:69], v29, s33, v[52:53]
	v_lshl_add_u64 v[50:51], v[52:53], 0, v[50:51]
	v_mad_u64_u32 v[50:51], s[68:69], v28, 1, v[50:51]
	v_lshlrev_b64 v[48:49], 2, v[28:29]
	v_add_u32_e32 v51, v29, v51
	v_lshrrev_b64 v[52:53], 15, v[50:51]
	v_lshrrev_b32_e32 v32, 31, v51
	v_ashrrev_i32_e32 v1, 31, v49
	v_lshl_add_u64 v[50:51], v[52:53], 0, v[32:33]
	v_mul_lo_u32 v32, v1, s33
	v_mad_u64_u32 v[52:53], s[68:69], v1, s60, 0
	v_add3_u32 v53, v53, v32, v52
	v_mad_u64_u32 v[52:53], s[68:69], v48, -1, v[52:53]
	v_alignbit_b32 v1, v29, v28, 30
	v_sub_u32_e32 v28, v53, v1
	v_mul_hi_u32 v32, v48, s60
	v_sub_u32_e32 v53, v28, v48
	v_mad_u64_u32 v[28:29], s[68:69], v1, s60, v[32:33]
	v_mov_b32_e32 v32, v29
	v_mov_b32_e32 v29, v33
	v_mad_u64_u32 v[28:29], s[68:69], v48, s33, v[28:29]
	v_mov_b32_e32 v28, v29
	v_mov_b32_e32 v29, v33
	v_lshl_add_u64 v[28:29], v[32:33], 0, v[28:29]
	v_mad_u64_u32 v[28:29], s[68:69], v1, s33, v[28:29]
	v_lshl_add_u64 v[28:29], v[28:29], 0, v[52:53]
	v_lshlrev_b64 v[22:23], 20, v[24:25]
	v_mad_u64_u32 v[28:29], s[68:69], v48, 1, v[28:29]
	v_lshl_add_u64 v[22:23], s[36:37], 0, v[22:23]
	v_add_u32_e32 v29, v1, v29
	v_lshl_add_u64 v[12:13], v[12:13], 2, v[22:23]
	v_ashrrev_i64 v[52:53], 17, v[28:29]
	v_lshrrev_b32_e32 v32, 31, v29
	v_add_co_u32_e32 v12, vcc, s62, v12
	v_lshl_add_u64 v[28:29], v[52:53], 0, v[32:33]
	s_nop 0
	v_addc_co_u32_e32 v13, vcc, 0, v13, vcc
	v_mad_u64_u32 v[52:53], s[68:69], v28, s61, 0
	v_mad_i32_i24 v1, v29, s61, v53
	v_sub_co_u32_e32 v28, vcc, v48, v52
	global_load_dwordx4 v[14:17], v[2:3], off nt
	s_nop 0
	global_load_dwordx4 v[2:5], v[4:5], off nt
	v_subb_co_u32_e32 v29, vcc, v49, v1, vcc
	v_lshlrev_b64 v[48:49], 20, v[50:51]
	v_lshl_add_u64 v[48:49], s[36:37], 0, v[48:49]
	v_ashrrev_i32_e32 v1, 31, v27
	v_lshl_add_u64 v[28:29], v[28:29], 2, v[48:49]
	v_mul_lo_u32 v32, v1, s33
	v_mad_u64_u32 v[48:49], s[68:69], v1, s60, 0
	v_add3_u32 v49, v49, v32, v48
	v_mul_hi_u32 v32, v26, s60
	v_mad_u64_u32 v[50:51], s[68:69], v27, s60, v[32:33]
	v_mov_b32_e32 v32, v51
	v_mov_b32_e32 v51, v33
	v_mad_u64_u32 v[50:51], s[68:69], v26, s33, v[50:51]
	v_mad_u64_u32 v[48:49], s[68:69], v26, -1, v[48:49]
	v_mov_b32_e32 v50, v51
	v_mov_b32_e32 v51, v33
	v_sub_u32_e32 v1, v49, v27
	v_lshl_add_u64 v[50:51], v[32:33], 0, v[50:51]
	v_sub_u32_e32 v49, v1, v26
	v_mad_u64_u32 v[50:51], s[68:69], v27, s33, v[50:51]
	v_lshl_add_u64 v[48:49], v[50:51], 0, v[48:49]
	v_mad_u64_u32 v[48:49], s[68:69], v26, 1, v[48:49]
	v_add_u32_e32 v49, v27, v49
	v_lshrrev_b64 v[26:27], 15, v[48:49]
	v_lshrrev_b32_e32 v32, 31, v49
	v_ashrrev_i32_e32 v1, 31, v31
	v_lshl_add_u64 v[26:27], v[26:27], 0, v[32:33]
	v_mul_lo_u32 v32, v1, s33
	v_mad_u64_u32 v[48:49], s[68:69], v1, s60, 0
	v_add3_u32 v49, v49, v32, v48
	v_mul_hi_u32 v32, v30, s60
	v_mad_u64_u32 v[50:51], s[68:69], v31, s60, v[32:33]
	v_mov_b32_e32 v32, v51
	v_mov_b32_e32 v51, v33
	v_mad_u64_u32 v[50:51], s[68:69], v30, s33, v[50:51]
	v_mad_u64_u32 v[48:49], s[68:69], v30, -1, v[48:49]
	v_mov_b32_e32 v50, v51
	v_mov_b32_e32 v51, v33
	v_sub_u32_e32 v1, v49, v31
	v_lshl_add_u64 v[50:51], v[32:33], 0, v[50:51]
	v_sub_u32_e32 v49, v1, v30
	v_mad_u64_u32 v[50:51], s[68:69], v31, s33, v[50:51]
	v_lshl_add_u64 v[48:49], v[50:51], 0, v[48:49]
	v_mad_u64_u32 v[48:49], s[68:69], v30, 1, v[48:49]
	v_add_u32_e32 v49, v31, v49
	v_ashrrev_i64 v[50:51], 17, v[48:49]
	v_lshrrev_b32_e32 v32, 31, v49
	v_add_co_u32_e32 v28, vcc, s62, v28
	v_lshl_add_u64 v[48:49], v[50:51], 0, v[32:33]
	s_nop 0
	v_addc_co_u32_e32 v29, vcc, 0, v29, vcc
	v_mad_u64_u32 v[50:51], s[68:69], v48, s61, 0
	v_mad_i32_i24 v1, v49, s61, v51
	v_sub_co_u32_e32 v48, vcc, v30, v50
	v_lshlrev_b64 v[52:53], 20, v[26:27]
	s_nop 0
	v_subb_co_u32_e32 v49, vcc, v31, v1, vcc
	v_lshl_add_u64 v[26:27], s[36:37], 0, v[52:53]
	v_lshlrev_b64 v[54:55], 2, v[48:49]
	v_lshl_add_u64 v[26:27], v[26:27], 0, v[54:55]
	v_add_co_u32_e32 v26, vcc, 0x4000, v26
	global_load_dwordx4 v[18:21], v[6:7], off nt
	s_nop 0
	global_load_dwordx4 v[6:9], v[8:9], off nt
	s_nop 0
	global_load_dwordx4 v[22:25], v[10:11], off nt
	s_nop 0
	global_load_dwordx4 v[10:13], v[12:13], off nt
	v_addc_co_u32_e32 v27, vcc, 0, v27, vcc
	global_load_dwordx4 v[48:51], v[26:27], off nt
	s_nop 0
	global_load_dwordx4 v[26:29], v[28:29], off nt
	v_lshl_add_u64 v[52:53], s[28:29], 0, v[52:53]
	v_lshl_add_u64 v[52:53], v[52:53], 0, v[54:55]
	v_readlane_b32 s38, v241, 20
	v_readlane_b32 s39, v241, 21
	v_readlane_b32 s40, v241, 22
	v_readlane_b32 s41, v241, 23
	v_readlane_b32 s42, v241, 24
	v_readlane_b32 s43, v241, 25
	v_readlane_b32 s44, v241, 26
	v_readlane_b32 s45, v241, 27
	v_readlane_b32 s46, v241, 28
	v_readlane_b32 s47, v241, 29
	v_readlane_b32 s48, v241, 30
	v_readlane_b32 s49, v241, 31
	v_readlane_b32 s50, v241, 32
	v_readlane_b32 s51, v241, 33
	s_waitcnt vmcnt(1)
	global_store_dwordx4 v[52:53], v[48:51], off nt
	s_and_saveexec_b64 s[92:93], s[0:1]
	s_cbranch_execz .LBB0_154
	v_ashrrev_i32_e32 v1, 31, v35
	v_mul_lo_u32 v32, v1, s33
	v_mad_u64_u32 v[50:51], s[0:1], v1, s60, 0
	v_add3_u32 v51, v51, v32, v50
	v_mul_hi_u32 v32, v34, s60
	v_mad_u64_u32 v[52:53], s[0:1], v35, s60, v[32:33]
	v_mov_b32_e32 v32, v53
	v_mov_b32_e32 v53, v33
	v_mad_u64_u32 v[52:53], s[0:1], v34, s33, v[52:53]
	v_mad_u64_u32 v[50:51], s[0:1], v34, -1, v[50:51]
	v_mov_b32_e32 v52, v53
	v_mov_b32_e32 v53, v33
	v_sub_u32_e32 v1, v51, v35
	v_lshl_add_u64 v[52:53], v[32:33], 0, v[52:53]
	v_sub_u32_e32 v51, v1, v34
	v_mad_u64_u32 v[52:53], s[0:1], v35, s33, v[52:53]
	v_lshl_add_u64 v[50:51], v[52:53], 0, v[50:51]
	v_mad_u64_u32 v[50:51], s[0:1], v34, 1, v[50:51]
	v_lshl_add_u64 v[48:49], s[54:55], 0, v[30:31]
	v_add_u32_e32 v51, v35, v51
	v_lshrrev_b64 v[52:53], 15, v[50:51]
	v_lshrrev_b32_e32 v32, 31, v51
	v_ashrrev_i32_e32 v1, 31, v49
	v_lshl_add_u64 v[50:51], v[52:53], 0, v[32:33]
	v_mul_lo_u32 v32, v1, s33
	v_mad_u64_u32 v[52:53], s[0:1], v1, s60, 0
	v_add3_u32 v53, v53, v32, v52
	v_mul_hi_u32 v32, v48, s60
	v_mad_u64_u32 v[54:55], s[0:1], v49, s60, v[32:33]
	v_mov_b32_e32 v32, v55
	v_mov_b32_e32 v55, v33
	v_mad_u64_u32 v[54:55], s[0:1], v48, s33, v[54:55]
	v_mad_u64_u32 v[52:53], s[0:1], v48, -1, v[52:53]
	v_mov_b32_e32 v54, v55
	v_mov_b32_e32 v55, v33
	v_sub_u32_e32 v1, v53, v49
	v_lshl_add_u64 v[54:55], v[32:33], 0, v[54:55]
	v_sub_u32_e32 v53, v1, v48
	v_mad_u64_u32 v[54:55], s[0:1], v49, s33, v[54:55]
	v_lshl_add_u64 v[52:53], v[54:55], 0, v[52:53]
	v_mad_u64_u32 v[52:53], s[0:1], v48, 1, v[52:53]
	v_add_u32_e32 v53, v49, v53
	v_ashrrev_i64 v[54:55], 17, v[52:53]
	v_lshrrev_b32_e32 v32, 31, v53
	v_lshl_add_u64 v[52:53], v[54:55], 0, v[32:33]
	v_mad_u64_u32 v[54:55], s[0:1], v52, s61, 0
	v_mad_i32_i24 v1, v53, s61, v55
	v_sub_co_u32_e32 v48, vcc, v48, v54
	v_lshlrev_b64 v[50:51], 20, v[50:51]
	s_nop 0
	v_subb_co_u32_e32 v49, vcc, v49, v1, vcc
	v_lshl_add_u64 v[50:51], s[28:29], 0, v[50:51]
	v_lshl_add_u64 v[48:49], v[48:49], 2, v[50:51]
	global_store_dwordx4 v[48:49], v[14:17], off nt
	s_or_b64 exec, exec, s[92:93]
	s_and_saveexec_b64 s[0:1], s[4:5]
	s_cbranch_execnz .LBB0_155

.LBB0_150:
	v_ashrrev_i32_e32 v1, 31, v39
	v_mul_lo_u32 v14, v1, s33
	v_mad_u64_u32 v[4:5], s[4:5], v1, s60, 0
	v_mul_hi_u32 v32, v38, s60
	v_add3_u32 v5, v5, v14, v4
	v_mad_u64_u32 v[14:15], s[4:5], v39, s60, v[32:33]
	v_mov_b32_e32 v32, v15
	v_mov_b32_e32 v15, v33
	v_mad_u64_u32 v[14:15], s[4:5], v38, s33, v[14:15]
	v_mad_u64_u32 v[4:5], s[4:5], v38, -1, v[4:5]
	v_mov_b32_e32 v14, v15
	v_mov_b32_e32 v15, v33
	v_sub_u32_e32 v1, v5, v39
	v_lshl_add_u64 v[14:15], v[32:33], 0, v[14:15]
	v_sub_u32_e32 v5, v1, v38
	v_mad_u64_u32 v[14:15], s[4:5], v39, s33, v[14:15]
	v_lshl_add_u64 v[4:5], v[14:15], 0, v[4:5]
	v_mad_u64_u32 v[4:5], s[4:5], v38, 1, v[4:5]
	v_lshl_add_u64 v[2:3], s[52:53], 0, v[30:31]
	v_add_u32_e32 v5, v39, v5
	v_lshrrev_b64 v[14:15], 15, v[4:5]
	v_lshrrev_b32_e32 v32, 31, v5
	v_ashrrev_i32_e32 v1, 31, v3
	v_lshl_add_u64 v[4:5], v[14:15], 0, v[32:33]
	v_mul_lo_u32 v16, v1, s33
	v_mad_u64_u32 v[14:15], s[4:5], v1, s60, 0
	v_mul_hi_u32 v32, v2, s60
	v_add3_u32 v15, v15, v16, v14
	v_mad_u64_u32 v[16:17], s[4:5], v3, s60, v[32:33]
	v_mov_b32_e32 v32, v17
	v_mov_b32_e32 v17, v33
	v_mad_u64_u32 v[16:17], s[4:5], v2, s33, v[16:17]
	v_mad_u64_u32 v[14:15], s[4:5], v2, -1, v[14:15]
	v_mov_b32_e32 v16, v17
	v_mov_b32_e32 v17, v33
	v_sub_u32_e32 v1, v15, v3
	v_lshl_add_u64 v[16:17], v[32:33], 0, v[16:17]
	v_sub_u32_e32 v15, v1, v2
	v_mad_u64_u32 v[16:17], s[4:5], v3, s33, v[16:17]
	v_lshl_add_u64 v[14:15], v[16:17], 0, v[14:15]
	v_mad_u64_u32 v[14:15], s[4:5], v2, 1, v[14:15]
	v_add_u32_e32 v15, v3, v15
	v_ashrrev_i64 v[16:17], 17, v[14:15]
	v_lshrrev_b32_e32 v32, 31, v15
	v_lshl_add_u64 v[14:15], v[16:17], 0, v[32:33]
	v_mad_u64_u32 v[16:17], s[4:5], v14, s61, 0
	v_mad_i32_i24 v1, v15, s61, v17
	v_sub_co_u32_e32 v2, vcc, v2, v16
	v_lshlrev_b64 v[4:5], 20, v[4:5]
	s_nop 0
	v_subb_co_u32_e32 v3, vcc, v3, v1, vcc
	v_lshl_add_u64 v[4:5], s[28:29], 0, v[4:5]
	v_lshl_add_u64 v[2:3], v[2:3], 2, v[4:5]
	global_store_dwordx4 v[2:3], v[18:21], off nt
	s_or_b64 exec, exec, s[0:1]
	s_and_saveexec_b64 s[0:1], s[8:9]
	s_cbranch_execnz .LBB0_157

.LBB0_152:
	v_ashrrev_i32_e32 v1, 31, v43
	v_mul_lo_u32 v6, v1, s33
	v_mad_u64_u32 v[4:5], s[4:5], v1, s60, 0
	v_mul_hi_u32 v32, v42, s60
	v_add3_u32 v5, v5, v6, v4
	v_mad_u64_u32 v[6:7], s[4:5], v43, s60, v[32:33]
	v_mov_b32_e32 v32, v7
	v_mov_b32_e32 v7, v33
	v_mad_u64_u32 v[6:7], s[4:5], v42, s33, v[6:7]
	v_mad_u64_u32 v[4:5], s[4:5], v42, -1, v[4:5]
	v_mov_b32_e32 v6, v7
	v_mov_b32_e32 v7, v33
	v_sub_u32_e32 v1, v5, v43
	v_lshl_add_u64 v[6:7], v[32:33], 0, v[6:7]
	v_sub_u32_e32 v5, v1, v42
	v_mad_u64_u32 v[6:7], s[4:5], v43, s33, v[6:7]
	v_lshl_add_u64 v[4:5], v[6:7], 0, v[4:5]
	v_mad_u64_u32 v[4:5], s[4:5], v42, 1, v[4:5]
	v_lshl_add_u64 v[2:3], s[64:65], 0, v[30:31]
	v_add_u32_e32 v5, v43, v5
	v_lshrrev_b64 v[6:7], 15, v[4:5]
	v_lshrrev_b32_e32 v32, 31, v5
	v_ashrrev_i32_e32 v1, 31, v3
	v_lshl_add_u64 v[4:5], v[6:7], 0, v[32:33]
	v_mul_lo_u32 v8, v1, s33
	v_mad_u64_u32 v[6:7], s[4:5], v1, s60, 0
	v_mul_hi_u32 v32, v2, s60
	v_add3_u32 v7, v7, v8, v6
	v_mad_u64_u32 v[8:9], s[4:5], v3, s60, v[32:33]
	v_mov_b32_e32 v32, v9
	v_mov_b32_e32 v9, v33
	v_mad_u64_u32 v[8:9], s[4:5], v2, s33, v[8:9]
	v_mad_u64_u32 v[6:7], s[4:5], v2, -1, v[6:7]
	v_mov_b32_e32 v8, v9
	v_mov_b32_e32 v9, v33
	v_sub_u32_e32 v1, v7, v3
	v_lshl_add_u64 v[8:9], v[32:33], 0, v[8:9]
	v_sub_u32_e32 v7, v1, v2
	v_mad_u64_u32 v[8:9], s[4:5], v3, s33, v[8:9]
	v_lshl_add_u64 v[6:7], v[8:9], 0, v[6:7]
	v_mad_u64_u32 v[6:7], s[4:5], v2, 1, v[6:7]
	v_add_u32_e32 v7, v3, v7
	v_ashrrev_i64 v[8:9], 17, v[6:7]
	v_lshrrev_b32_e32 v32, 31, v7
	v_lshl_add_u64 v[6:7], v[8:9], 0, v[32:33]
	v_mad_u64_u32 v[8:9], s[4:5], v6, s61, 0
	v_mad_i32_i24 v1, v7, s61, v9
	v_sub_co_u32_e32 v2, vcc, v2, v8
	v_lshlrev_b64 v[4:5], 20, v[4:5]
	s_nop 0
	v_subb_co_u32_e32 v3, vcc, v3, v1, vcc
	v_lshl_add_u64 v[4:5], s[28:29], 0, v[4:5]
	v_lshl_add_u64 v[2:3], v[2:3], 2, v[4:5]
	global_store_dwordx4 v[2:3], v[22:25], off nt
	s_or_b64 exec, exec, s[0:1]
	s_and_saveexec_b64 s[0:1], s[14:15]
	s_cbranch_execnz .LBB0_159

.LBB0_155:
	v_ashrrev_i32_e32 v1, 31, v37
	v_mul_lo_u32 v32, v1, s33
	v_mad_u64_u32 v[16:17], s[4:5], v1, s60, 0
	v_add3_u32 v17, v17, v32, v16
	v_mul_hi_u32 v32, v36, s60
	v_mad_u64_u32 v[48:49], s[4:5], v37, s60, v[32:33]
	v_mov_b32_e32 v32, v49
	v_mov_b32_e32 v49, v33
	v_mad_u64_u32 v[48:49], s[4:5], v36, s33, v[48:49]
	v_mad_u64_u32 v[16:17], s[4:5], v36, -1, v[16:17]
	v_mov_b32_e32 v48, v49
	v_mov_b32_e32 v49, v33
	v_sub_u32_e32 v1, v17, v37
	v_lshl_add_u64 v[48:49], v[32:33], 0, v[48:49]
	v_sub_u32_e32 v17, v1, v36
	v_mad_u64_u32 v[48:49], s[4:5], v37, s33, v[48:49]
	v_lshl_add_u64 v[16:17], v[48:49], 0, v[16:17]
	v_mad_u64_u32 v[16:17], s[4:5], v36, 1, v[16:17]
	v_lshl_add_u64 v[14:15], s[70:71], 0, v[30:31]
	v_add_u32_e32 v17, v37, v17
	v_lshrrev_b64 v[36:37], 15, v[16:17]
	v_lshrrev_b32_e32 v32, 31, v17
	v_ashrrev_i32_e32 v1, 31, v15
	v_lshl_add_u64 v[16:17], v[36:37], 0, v[32:33]
	v_mul_lo_u32 v32, v1, s33
	v_mad_u64_u32 v[36:37], s[4:5], v1, s60, 0
	v_add3_u32 v37, v37, v32, v36
	v_mul_hi_u32 v32, v14, s60
	v_mad_u64_u32 v[48:49], s[4:5], v15, s60, v[32:33]
	v_mov_b32_e32 v32, v49
	v_mov_b32_e32 v49, v33
	v_mad_u64_u32 v[48:49], s[4:5], v14, s33, v[48:49]
	v_mad_u64_u32 v[36:37], s[4:5], v14, -1, v[36:37]
	v_mov_b32_e32 v48, v49
	v_mov_b32_e32 v49, v33
	v_sub_u32_e32 v1, v37, v15
	v_lshl_add_u64 v[48:49], v[32:33], 0, v[48:49]
	v_sub_u32_e32 v37, v1, v14
	v_mad_u64_u32 v[48:49], s[4:5], v15, s33, v[48:49]
	v_lshl_add_u64 v[36:37], v[48:49], 0, v[36:37]
	v_mad_u64_u32 v[36:37], s[4:5], v14, 1, v[36:37]
	v_add_u32_e32 v37, v15, v37
	v_ashrrev_i64 v[48:49], 17, v[36:37]
	v_lshrrev_b32_e32 v32, 31, v37
	v_lshl_add_u64 v[36:37], v[48:49], 0, v[32:33]
	v_mad_u64_u32 v[48:49], s[4:5], v36, s61, 0
	v_mad_i32_i24 v1, v37, s61, v49
	v_sub_co_u32_e32 v14, vcc, v14, v48
	v_lshlrev_b64 v[16:17], 20, v[16:17]
	s_nop 0
	v_subb_co_u32_e32 v15, vcc, v15, v1, vcc
	v_lshl_add_u64 v[16:17], s[28:29], 0, v[16:17]
	v_lshl_add_u64 v[14:15], v[14:15], 2, v[16:17]
	global_store_dwordx4 v[14:15], v[2:5], off nt
	s_or_b64 exec, exec, s[0:1]
	s_and_saveexec_b64 s[0:1], s[6:7]
	s_cbranch_execnz .LBB0_150

.LBB0_157:
	v_ashrrev_i32_e32 v1, 31, v41
	v_mul_lo_u32 v14, v1, s33
	v_mad_u64_u32 v[4:5], s[4:5], v1, s60, 0
	v_mul_hi_u32 v32, v40, s60
	v_add3_u32 v5, v5, v14, v4
	v_mad_u64_u32 v[14:15], s[4:5], v41, s60, v[32:33]
	v_mov_b32_e32 v32, v15
	v_mov_b32_e32 v15, v33
	v_mad_u64_u32 v[14:15], s[4:5], v40, s33, v[14:15]
	v_mad_u64_u32 v[4:5], s[4:5], v40, -1, v[4:5]
	v_mov_b32_e32 v14, v15
	v_mov_b32_e32 v15, v33
	v_sub_u32_e32 v1, v5, v41
	v_lshl_add_u64 v[14:15], v[32:33], 0, v[14:15]
	v_sub_u32_e32 v5, v1, v40
	v_mad_u64_u32 v[14:15], s[4:5], v41, s33, v[14:15]
	v_lshl_add_u64 v[4:5], v[14:15], 0, v[4:5]
	v_mad_u64_u32 v[4:5], s[4:5], v40, 1, v[4:5]
	v_lshl_add_u64 v[2:3], s[56:57], 0, v[30:31]
	v_add_u32_e32 v5, v41, v5
	v_lshrrev_b64 v[14:15], 15, v[4:5]
	v_lshrrev_b32_e32 v32, 31, v5
	v_ashrrev_i32_e32 v1, 31, v3
	v_lshl_add_u64 v[4:5], v[14:15], 0, v[32:33]
	v_mul_lo_u32 v16, v1, s33
	v_mad_u64_u32 v[14:15], s[4:5], v1, s60, 0
	v_mul_hi_u32 v32, v2, s60
	v_add3_u32 v15, v15, v16, v14
	v_mad_u64_u32 v[16:17], s[4:5], v3, s60, v[32:33]
	v_mov_b32_e32 v32, v17
	v_mov_b32_e32 v17, v33
	v_mad_u64_u32 v[16:17], s[4:5], v2, s33, v[16:17]
	v_mad_u64_u32 v[14:15], s[4:5], v2, -1, v[14:15]
	v_mov_b32_e32 v16, v17
	v_mov_b32_e32 v17, v33
	v_sub_u32_e32 v1, v15, v3
	v_lshl_add_u64 v[16:17], v[32:33], 0, v[16:17]
	v_sub_u32_e32 v15, v1, v2
	v_mad_u64_u32 v[16:17], s[4:5], v3, s33, v[16:17]
	v_lshl_add_u64 v[14:15], v[16:17], 0, v[14:15]
	v_mad_u64_u32 v[14:15], s[4:5], v2, 1, v[14:15]
	v_add_u32_e32 v15, v3, v15
	v_ashrrev_i64 v[16:17], 17, v[14:15]
	v_lshrrev_b32_e32 v32, 31, v15
	v_lshl_add_u64 v[14:15], v[16:17], 0, v[32:33]
	v_mad_u64_u32 v[16:17], s[4:5], v14, s61, 0
	v_mad_i32_i24 v1, v15, s61, v17
	v_sub_co_u32_e32 v2, vcc, v2, v16
	v_lshlrev_b64 v[4:5], 20, v[4:5]
	s_nop 0
	v_subb_co_u32_e32 v3, vcc, v3, v1, vcc
	v_lshl_add_u64 v[4:5], s[28:29], 0, v[4:5]
	v_lshl_add_u64 v[2:3], v[2:3], 2, v[4:5]
	global_store_dwordx4 v[2:3], v[6:9], off nt
	s_or_b64 exec, exec, s[0:1]
	s_and_saveexec_b64 s[0:1], s[12:13]
	s_cbranch_execnz .LBB0_152

.LBB0_159:
	v_ashrrev_i32_e32 v1, 31, v45
	v_mul_lo_u32 v6, v1, s33
	v_mad_u64_u32 v[4:5], s[4:5], v1, s60, 0
	v_mul_hi_u32 v32, v44, s60
	v_add3_u32 v5, v5, v6, v4
	v_mad_u64_u32 v[6:7], s[4:5], v45, s60, v[32:33]
	v_mov_b32_e32 v32, v7
	v_mov_b32_e32 v7, v33
	v_mad_u64_u32 v[6:7], s[4:5], v44, s33, v[6:7]
	v_mad_u64_u32 v[4:5], s[4:5], v44, -1, v[4:5]
	v_mov_b32_e32 v6, v7
	v_mov_b32_e32 v7, v33
	v_sub_u32_e32 v1, v5, v45
	v_lshl_add_u64 v[6:7], v[32:33], 0, v[6:7]
	v_sub_u32_e32 v5, v1, v44
	v_mad_u64_u32 v[6:7], s[4:5], v45, s33, v[6:7]
	v_lshl_add_u64 v[4:5], v[6:7], 0, v[4:5]
	v_mad_u64_u32 v[4:5], s[4:5], v44, 1, v[4:5]
	v_lshl_add_u64 v[2:3], s[2:3], 0, v[30:31]
	v_add_u32_e32 v5, v45, v5
	v_lshrrev_b64 v[6:7], 15, v[4:5]
	v_lshrrev_b32_e32 v32, 31, v5
	v_ashrrev_i32_e32 v1, 31, v3
	v_lshl_add_u64 v[4:5], v[6:7], 0, v[32:33]
	v_mul_lo_u32 v8, v1, s33
	v_mad_u64_u32 v[6:7], s[4:5], v1, s60, 0
	v_mul_hi_u32 v32, v2, s60
	v_add3_u32 v7, v7, v8, v6
	v_mad_u64_u32 v[8:9], s[4:5], v3, s60, v[32:33]
	v_mov_b32_e32 v32, v9
	v_mov_b32_e32 v9, v33
	v_mad_u64_u32 v[8:9], s[4:5], v2, s33, v[8:9]
	v_mad_u64_u32 v[6:7], s[4:5], v2, -1, v[6:7]
	v_mov_b32_e32 v8, v9
	v_mov_b32_e32 v9, v33
	v_sub_u32_e32 v1, v7, v3
	v_lshl_add_u64 v[8:9], v[32:33], 0, v[8:9]
	v_sub_u32_e32 v7, v1, v2
	v_mad_u64_u32 v[8:9], s[4:5], v3, s33, v[8:9]
	v_lshl_add_u64 v[6:7], v[8:9], 0, v[6:7]
	v_mad_u64_u32 v[6:7], s[4:5], v2, 1, v[6:7]
	v_add_u32_e32 v7, v3, v7
	v_ashrrev_i64 v[8:9], 17, v[6:7]
	v_lshrrev_b32_e32 v32, 31, v7
	v_lshl_add_u64 v[6:7], v[8:9], 0, v[32:33]
	v_mad_u64_u32 v[8:9], s[4:5], v6, s61, 0
	v_mad_i32_i24 v1, v7, s61, v9
	v_sub_co_u32_e32 v2, vcc, v2, v8
	v_lshlrev_b64 v[4:5], 20, v[4:5]
	s_nop 0
	v_subb_co_u32_e32 v3, vcc, v3, v1, vcc
	v_lshl_add_u64 v[4:5], s[28:29], 0, v[4:5]
	v_lshl_add_u64 v[2:3], v[2:3], 2, v[4:5]
	global_store_dwordx4 v[2:3], v[10:13], off nt
	s_or_b64 exec, exec, s[0:1]
	s_and_saveexec_b64 s[0:1], s[16:17]
	s_cbranch_execz .LBB0_146
.LBB0_160:
	v_ashrrev_i32_e32 v1, 31, v47
	v_mul_lo_u32 v6, v1, s33
	v_mad_u64_u32 v[4:5], s[4:5], v1, s60, 0
	v_mul_hi_u32 v32, v46, s60
	v_add3_u32 v5, v5, v6, v4
	v_mad_u64_u32 v[6:7], s[4:5], v47, s60, v[32:33]
	v_mov_b32_e32 v32, v7
	v_mov_b32_e32 v7, v33
	v_mad_u64_u32 v[6:7], s[4:5], v46, s33, v[6:7]
	v_mad_u64_u32 v[4:5], s[4:5], v46, -1, v[4:5]
	v_mov_b32_e32 v6, v7
	v_mov_b32_e32 v7, v33
	v_sub_u32_e32 v1, v5, v47
	v_lshl_add_u64 v[6:7], v[32:33], 0, v[6:7]
	v_sub_u32_e32 v5, v1, v46
	v_mad_u64_u32 v[6:7], s[4:5], v47, s33, v[6:7]
	v_lshl_add_u64 v[4:5], v[6:7], 0, v[4:5]
	v_mad_u64_u32 v[4:5], s[4:5], v46, 1, v[4:5]
	v_lshl_add_u64 v[2:3], s[82:83], 0, v[30:31]
	v_add_u32_e32 v5, v47, v5
	v_lshrrev_b64 v[6:7], 15, v[4:5]
	v_lshrrev_b32_e32 v32, 31, v5
	v_ashrrev_i32_e32 v1, 31, v3
	v_lshl_add_u64 v[4:5], v[6:7], 0, v[32:33]
	v_mul_lo_u32 v8, v1, s33
	v_mad_u64_u32 v[6:7], s[4:5], v1, s60, 0
	v_mul_hi_u32 v32, v2, s60
	v_add3_u32 v7, v7, v8, v6
	v_mad_u64_u32 v[8:9], s[4:5], v3, s60, v[32:33]
	v_mov_b32_e32 v32, v9
	v_mov_b32_e32 v9, v33
	v_mad_u64_u32 v[8:9], s[4:5], v2, s33, v[8:9]
	v_mad_u64_u32 v[6:7], s[4:5], v2, -1, v[6:7]
	v_mov_b32_e32 v8, v9
	v_mov_b32_e32 v9, v33
	v_sub_u32_e32 v1, v7, v3
	v_lshl_add_u64 v[8:9], v[32:33], 0, v[8:9]
	v_sub_u32_e32 v7, v1, v2
	v_mad_u64_u32 v[8:9], s[4:5], v3, s33, v[8:9]
	v_lshl_add_u64 v[6:7], v[8:9], 0, v[6:7]
	v_mad_u64_u32 v[6:7], s[4:5], v2, 1, v[6:7]
	v_add_u32_e32 v7, v3, v7
	v_ashrrev_i64 v[8:9], 17, v[6:7]
	v_lshrrev_b32_e32 v32, 31, v7
	v_lshl_add_u64 v[6:7], v[8:9], 0, v[32:33]
	v_mad_u64_u32 v[8:9], s[4:5], v6, s61, 0
	v_mad_i32_i24 v1, v7, s61, v9
	v_sub_co_u32_e32 v2, vcc, v2, v8
	v_lshlrev_b64 v[4:5], 20, v[4:5]
	s_nop 0
	v_subb_co_u32_e32 v3, vcc, v3, v1, vcc
	v_lshl_add_u64 v[4:5], s[28:29], 0, v[4:5]
	v_lshl_add_u64 v[2:3], v[2:3], 2, v[4:5]
	s_waitcnt vmcnt(1)
	global_store_dwordx4 v[2:3], v[26:29], off nt
	s_branch .LBB0_146

.LBB0_1568:
	s_or_b64 exec, exec, s[8:9]
	s_lshl_b32 s14, s2, 7
	s_ashr_i32 s15, s14, 31
	v_lshl_add_u64 v[18:19], s[14:15], 2, v[18:19]
	v_lshl_add_u64 v[30:31], v[18:19], 0, v[164:165]
	global_load_dwordx4 v[18:21], v[30:31], off nt
	global_load_dwordx4 v[22:25], v[30:31], off offset:16 nt
	global_load_dwordx4 v[26:29], v[30:31], off offset:256 nt
	s_nop 0
	global_load_dwordx4 v[30:33], v[30:31], off offset:272 nt
	s_cmp_gt_i32 s30, -1
	s_cselect_b64 s[20:21], -1, 0
	s_and_b64 s[8:9], s[20:21], exec
	s_cselect_b32 s3, s30, 0
	v_lshl_add_u32 v1, s3, 6, v170
	v_cmp_lt_i32_e32 vcc, s57, v1
	s_waitcnt vmcnt(3)
	v_cvt_pk_bf16_f32 v18, v18, v19
	v_cvt_pk_bf16_f32 v19, v20, v21
	s_waitcnt vmcnt(2)
	v_cvt_pk_bf16_f32 v20, v22, v23
	v_cvt_pk_bf16_f32 v21, v24, v25
	s_waitcnt vmcnt(1)
	v_cvt_pk_bf16_f32 v22, v26, v27
	v_cvt_pk_bf16_f32 v23, v28, v29
	s_waitcnt vmcnt(0)
	v_cvt_pk_bf16_f32 v24, v30, v31
	v_cvt_pk_bf16_f32 v25, v32, v33
	ds_write_b128 v183, v[18:21]
	ds_write_b128 v183, v[22:25] offset:10240
	s_and_saveexec_b64 s[8:9], vcc
	s_xor_b64 s[8:9], exec, s[8:9]
	s_cbranch_execz .LBB0_1570
	v_min_u32_e32 v1, 0x2007, v1
	s_lshl_b64 s[22:23], s[6:7], 14
	v_readlane_b32 s24, v240, 36
	v_add_u32_e32 v18, 0xffffe000, v1
	v_mov_b32_e32 v19, v165
	s_add_u32 s22, s24, s22
	v_readlane_b32 s24, v240, 37
	s_addc_u32 s23, s24, s23
	v_lshlrev_b64 v[18:19], 11, v[18:19]
	v_lshl_add_u64 v[18:19], s[22:23], 0, v[18:19]

.LBB0_1572:
	s_or_b64 exec, exec, s[8:9]
	v_lshl_add_u64 v[18:19], s[14:15], 2, v[18:19]
	v_lshl_add_u64 v[18:19], v[18:19], 0, v[164:165]
	global_load_dwordx4 v[82:85], v[18:19], off offset:16 nt
	global_load_dwordx4 v[86:89], v[18:19], off nt
	global_load_dwordx4 v[62:65], v[18:19], off offset:272 nt
	global_load_dwordx4 v[74:77], v[18:19], off offset:256 nt
	s_max_i32 s3, s29, 0
	v_lshl_add_u32 v1, s3, 6, v170
	v_cmp_lt_i32_e32 vcc, s57, v1
	s_waitcnt lgkmcnt(0)
	s_barrier
	s_and_saveexec_b64 s[8:9], vcc
	s_xor_b64 s[8:9], exec, s[8:9]
	s_cbranch_execz .LBB0_1574
	v_min_u32_e32 v1, 0x2007, v1
	s_lshl_b64 s[22:23], s[6:7], 14
	v_readlane_b32 s24, v240, 36
	v_add_u32_e32 v18, 0xffffe000, v1
	v_mov_b32_e32 v19, v165
	s_add_u32 s22, s24, s22
	v_readlane_b32 s24, v240, 37
	s_addc_u32 s23, s24, s23
	v_lshlrev_b64 v[18:19], 11, v[18:19]
	v_lshl_add_u64 v[18:19], s[22:23], 0, v[18:19]

.LBB0_1576:
	s_or_b64 exec, exec, s[8:9]
	v_lshl_add_u64 v[18:19], s[14:15], 2, v[18:19]
	v_lshl_add_u64 v[18:19], v[18:19], 0, v[164:165]
	global_load_dwordx4 v[66:69], v[18:19], off offset:16 nt
	global_load_dwordx4 v[78:81], v[18:19], off nt
	global_load_dwordx4 v[58:61], v[18:19], off offset:272 nt
	global_load_dwordx4 v[70:73], v[18:19], off offset:256 nt
	v_cndmask_b32_e64 v1, 0, 1, s[12:13]
	v_cmp_ne_u32_e64 s[8:9], 1, v1
	s_andn2_b64 vcc, exec, s[12:13]
	v_or_b32_e32 v1, 0x2000, v179
	s_cbranch_vccnz .LBB0_1579
	v_and_b32_e32 v18, 48, v176
	v_add3_u32 v22, 0, v18, v184
	ds_read_b128 v[18:21], v22
	ds_read_b128 v[22:25], v22 offset:64
	s_setprio 1
	s_waitcnt lgkmcnt(1)
	v_mfma_f32_16x16x32_bf16 v[26:29], v[18:21], v[6:9], 0
	s_mov_b32 s76, s77
	s_mov_b32 s78, s77
	s_mov_b32 s79, s77
	v_mfma_f32_16x16x32_bf16 v[18:21], v[18:21], v[14:17], 0
	s_waitcnt lgkmcnt(0)
	v_mfma_f32_16x16x32_bf16 v[26:29], v[22:25], v[2:5], v[26:29]
	v_mfma_f32_16x16x32_bf16 v[30:33], v[22:25], v[10:13], v[18:21]
	s_setprio 0
	s_nop 3
	v_lshlrev_b32_e32 v18, 2, v138
	s_movk_i32 s3, 0xdfff
	v_sub_u32_e32 v19, v179, v18
	v_xad_u32 v21, v18, s3, v1
	v_cvt_f32_u32_e32 v20, v19
	v_cmp_lt_i32_e64 s[12:13], -1, v21
	v_cvt_f32_u32_e32 v21, v21
	v_or_b32_e32 v24, 0x2003, v18
	v_or_b32_e32 v25, 0x2002, v18
	v_sub_u32_e32 v25, v1, v25
	v_sub_u32_e32 v24, v1, v24
	v_cmp_lt_i32_e32 vcc, -1, v19
	v_fma_f32 v19, -v168, v20, v26
	v_fma_f32 v22, -v168, v21, v27
	v_fma_f32 v20, -v166, v20, v30
	v_fma_f32 v21, -v166, v21, v31
	v_cvt_f32_u32_e32 v31, v24
	v_cvt_f32_u32_e32 v30, v25
	v_cndmask_b32_e32 v19, v173, v19, vcc
	v_cndmask_b32_e64 v22, v173, v22, s[12:13]
	v_cndmask_b32_e32 v20, v173, v20, vcc
	v_cndmask_b32_e64 v21, v173, v21, s[12:13]
	v_cmp_lt_i32_e32 vcc, -1, v25
	v_cmp_lt_i32_e64 s[12:13], -1, v24
	v_pk_fma_f32 v[24:25], v[168:169], v[30:31], v[28:29] op_sel_hi:[0,1,1] neg_lo:[1,0,0] neg_hi:[1,0,0]
	v_max_f32_e32 v23, 0xf149f2ca, v19
	v_cndmask_b32_e32 v26, v173, v24, vcc
	v_cndmask_b32_e64 v25, v173, v25, s[12:13]
	v_max3_f32 v23, v23, v22, v26
	v_max3_f32 v23, v23, v25, s96
	v_mov_b32_e32 v24, v23
	s_nop 1
	v_permlane16_swap_b32_e32 v23, v24
	v_max_f32_e32 v24, v24, v24
	v_max_f32_e32 v23, v23, v23
	v_max_f32_e32 v23, v23, v24
	v_mov_b32_e32 v24, v23
	s_nop 1
	v_permlane32_swap_b32_e32 v23, v24
	v_max_f32_e32 v24, v24, v24
	v_max_f32_e32 v23, v23, v23
	v_pk_fma_f32 v[30:31], v[166:167], v[30:31], v[32:33] op_sel_hi:[0,1,1] neg_lo:[1,0,0] neg_hi:[1,0,0]
	v_max_f32_e32 v27, 0xf149f2ca, v20
	v_max_f32_e32 v28, v23, v24
	v_cndmask_b32_e32 v23, v173, v30, vcc
	v_cndmask_b32_e64 v24, v173, v31, s[12:13]
	v_max3_f32 v27, v27, v21, v23
	v_max3_f32 v27, v27, v24, s96
	v_mov_b32_e32 v29, v27
	s_nop 1
	v_permlane16_swap_b32_e32 v27, v29
	v_max_f32_e32 v29, v29, v29
	v_max_f32_e32 v27, v27, v27
	v_max_f32_e32 v27, v27, v29
	v_mov_b32_e32 v29, v27
	s_nop 1
	v_permlane32_swap_b32_e32 v27, v29
	v_max_f32_e32 v29, v29, v29
	v_max_f32_e32 v27, v27, v27
	v_max_f32_e32 v27, v27, v29
	v_add_f32_e32 v29, 0x7149f2ca, v28
	v_add_f32_e32 v30, 0x7149f2ca, v27
	v_max_f32_e32 v29, v29, v30
	v_cmp_lt_f32_e32 vcc, s94, v29
	s_cbranch_vccz .LBB0_1580
	v_max_f32_e32 v28, v28, v28
	v_max_f32_e32 v128, 0xf149f2ca, v28
	v_sub_f32_e32 v28, 0xf149f2ca, v128
	v_exp_f32_e32 v30, v28
	v_sub_f32_e32 v28, v19, v128
	v_exp_f32_e32 v28, v28
	v_sub_f32_e32 v29, v22, v128
	v_exp_f32_e32 v29, v29
	v_cmp_lt_f32_e32 vcc, s97, v19
	s_movk_i32 s3, 0x2800
	s_nop 0
	v_cndmask_b32_e32 v19, 0, v28, vcc
	v_sub_f32_e32 v28, v25, v128
	v_cmp_lt_f32_e32 vcc, s97, v22
	v_exp_f32_e32 v28, v28
	s_nop 0
	v_cndmask_b32_e32 v22, 0, v29, vcc
	v_sub_f32_e32 v29, v26, v128
	v_exp_f32_e32 v29, v29
	v_cmp_lt_f32_e32 vcc, s97, v25
	s_nop 1
	v_cndmask_b32_e32 v25, 0, v28, vcc
	v_cvt_pk_bf16_f32 v28, v19, v22
	v_max_f32_e32 v19, v27, v27
	v_cmp_lt_f32_e32 vcc, s97, v26
	v_max_f32_e32 v129, 0xf149f2ca, v19
	v_sub_f32_e32 v22, v20, v129
	v_cndmask_b32_e32 v26, 0, v29, vcc
	v_cvt_pk_bf16_f32 v29, v26, v25
	v_exp_f32_e32 v22, v22
	v_sub_f32_e32 v25, v21, v129
	v_exp_f32_e32 v25, v25
	v_cmp_lt_f32_e32 vcc, s97, v20
	v_sub_f32_e32 v19, 0xf149f2ca, v129
	v_exp_f32_e32 v19, v19
	v_cndmask_b32_e32 v20, 0, v22, vcc
	v_cmp_lt_f32_e32 vcc, s97, v21
	v_sub_f32_e32 v22, v24, v129
	v_exp_f32_e32 v22, v22
	v_cndmask_b32_e32 v21, 0, v25, vcc
	v_sub_f32_e32 v25, v23, v129
	v_exp_f32_e32 v25, v25
	v_cmp_lt_f32_e32 vcc, s97, v24
	v_cmp_neq_f32_e64 s[12:13], 1.0, v19
	v_cvt_pk_bf16_f32 v20, v20, v21
	v_cndmask_b32_e32 v22, 0, v22, vcc
	v_cmp_lt_f32_e32 vcc, s97, v23
	v_mul_f32_e32 v19, 0, v19
	s_nop 0
	v_cndmask_b32_e32 v23, 0, v25, vcc
	v_cmp_neq_f32_e32 vcc, 1.0, v30
	s_or_b64 s[12:13], vcc, s[12:13]
	v_cvt_pk_bf16_f32 v21, v23, v22
	v_cndmask_b32_e64 v22, 0, 1, s[12:13]
	v_cmp_ne_u32_e32 vcc, 0, v22
	s_cmp_eq_u64 vcc, 0
	s_cselect_b64 s[12:13], -1, 0
	v_cndmask_b32_e64 v24, v19, 0, s[12:13]
	v_lshrrev_b32_e32 v19, 2, v178
	v_or_b32_e32 v18, v18, v19
	v_lshlrev_b32_e32 v19, 3, v178
	v_mad_u32_u24 v18, v18, s56, 0
	v_and_b32_e32 v19, 24, v19
	v_add3_u32 v18, v18, v19, s3
	ds_read_b64_tr_b16 v[36:37], v18 offset:0
	ds_read_b64_tr_b16 v[38:39], v18 offset:2560
	ds_read_b64_tr_b16 v[40:41], v18 offset:32
	ds_read_b64_tr_b16 v[42:43], v18 offset:2592
	ds_read_b64_tr_b16 v[44:45], v18 offset:64
	ds_read_b64_tr_b16 v[46:47], v18 offset:2624
	ds_read_b64_tr_b16 v[48:49], v18 offset:96
	ds_read_b64_tr_b16 v[50:51], v18 offset:2656
	ds_read_b64_tr_b16 v[52:53], v18 offset:5120
	ds_read_b64_tr_b16 v[54:55], v18 offset:7680
	ds_read_b64_tr_b16 v[90:91], v18 offset:5152
	ds_read_b64_tr_b16 v[92:93], v18 offset:7712
	ds_read_b64_tr_b16 v[94:95], v18 offset:5184
	ds_read_b64_tr_b16 v[96:97], v18 offset:7744
	ds_read_b64_tr_b16 v[98:99], v18 offset:5216
	ds_read_b64_tr_b16 v[100:101], v18 offset:7776
	v_mul_f32_e32 v22, 0, v30
	s_waitcnt lgkmcnt(8)
	v_cndmask_b32_e64 v32, v22, 0, s[12:13]
	v_mov_b32_e32 v25, v24
	v_mov_b32_e32 v26, v24
	v_mov_b32_e32 v27, v24
	v_mov_b32_e32 v33, v32
	v_mov_b32_e32 v34, v32
	v_mov_b32_e32 v35, v32
	s_setprio 1
	s_mov_b32 s82, s80
	s_mov_b32 s83, s80
	s_mov_b32 s81, s80
	v_mov_b64_e32 v[142:143], s[82:83]
	v_mov_b32_e32 v30, v165
	v_mov_b32_e32 v31, v165
	v_mov_b32_e32 v22, v165
	v_mov_b32_e32 v23, v165
	v_mov_b64_e32 v[140:141], s[80:81]
	v_mfma_f32_16x16x32_bf16 v[102:105], v[36:39], v[28:31], v[32:35]
	s_waitcnt lgkmcnt(0)
	v_mfma_f32_16x16x32_bf16 v[36:39], v[36:39], v[20:23], v[24:27]
	v_mfma_f32_16x16x32_bf16 v[106:109], v[40:43], v[28:31], v[32:35]
	v_mfma_f32_16x16x32_bf16 v[110:113], v[40:43], v[20:23], v[24:27]
	v_mfma_f32_16x16x32_bf16 v[114:117], v[44:47], v[28:31], v[32:35]
	v_mfma_f32_16x16x32_bf16 v[118:121], v[44:47], v[20:23], v[24:27]
	v_mfma_f32_16x16x32_bf16 v[130:133], v[48:51], v[28:31], v[32:35]
	v_mfma_f32_16x16x32_bf16 v[134:137], v[48:51], v[20:23], v[24:27]
	v_mfma_f32_16x16x32_bf16 v[144:147], v[140:143], v[28:31], v[32:35]
	v_mfma_f32_16x16x32_bf16 v[148:151], v[140:143], v[20:23], v[24:27]
	v_mov_b64_e32 v[154:155], s[78:79]
	v_mov_b64_e32 v[152:153], s[76:77]
	s_nop 1
	v_mfma_f32_16x16x32_bf16 v[46:49], v[52:55], v[152:155], v[102:105]
	v_mfma_f32_16x16x32_bf16 v[30:33], v[52:55], v[152:155], v[36:39]
	v_mfma_f32_16x16x32_bf16 v[42:45], v[90:93], v[152:155], v[106:109]
	v_mfma_f32_16x16x32_bf16 v[26:29], v[90:93], v[152:155], v[110:113]
	v_mfma_f32_16x16x32_bf16 v[38:41], v[94:97], v[152:155], v[114:117]
	v_mfma_f32_16x16x32_bf16 v[22:25], v[94:97], v[152:155], v[118:121]
	v_mfma_f32_16x16x32_bf16 v[34:37], v[98:101], v[152:155], v[130:133]
	v_mfma_f32_16x16x32_bf16 v[18:21], v[98:101], v[152:155], v[134:137]
	v_mfma_f32_16x16x32_bf16 v[54:57], v[140:143], v[152:155], v[144:147]
	v_mfma_f32_16x16x32_bf16 v[50:53], v[140:143], v[152:155], v[148:151]
	s_setprio 0
	s_branch .LBB0_1581

.LBB0_1597:
	s_or_b64 exec, exec, s[12:13]
	v_lshl_add_u64 v[58:59], s[14:15], 2, v[58:59]
	s_waitcnt vmcnt(0)
	v_lshl_add_u64 v[62:63], v[58:59], 0, v[164:165]
	global_load_dwordx4 v[66:69], v[62:63], off offset:16 nt
	global_load_dwordx4 v[70:73], v[62:63], off nt
	global_load_dwordx4 v[58:61], v[62:63], off offset:272 nt
	s_nop 0
	global_load_dwordx4 v[62:65], v[62:63], off offset:256 nt
	s_and_b64 vcc, exec, s[8:9]
	s_cbranch_vccnz .LBB0_1602
	s_lshr_b32 s12, s30, 3
	s_and_b32 s12, s12, 0x1ffffffc
	v_add_u32_e32 v82, s12, v182
	ds_read_b32 v82, v82 offset:16
	s_and_b32 s12, s30, 31
	s_waitcnt lgkmcnt(0)
	v_lshrrev_b32_e32 v83, s30, v82
	v_bfe_u32 v82, v82, s12, 1
	v_and_b32_e32 v83, 1, v83
	v_cmp_ne_u32_e32 vcc, 0, v82
	v_cmp_eq_u32_e64 s[12:13], 1, v83
	s_cbranch_vccz .LBB0_1602
	v_add_u32_e32 v123, v131, v184
	ds_read_b128 v[110:113], v123 offset:20480
	ds_read_b128 v[114:117], v123 offset:20544
	ds_read_b128 v[118:121], v123 offset:23040
	ds_read_b128 v[134:137], v123 offset:23104
	ds_read_b128 v[140:143], v123 offset:25600
	ds_read_b128 v[144:147], v123 offset:25664
	ds_read_b128 v[148:151], v123 offset:28160
	ds_read_b128 v[152:155], v123 offset:28224
	v_lshl_add_u32 v82, s30, 6, v130
	v_cvt_f32_i32_e32 v98, v82
	v_fma_f32 v82, v168, v98, -v128
	v_cndmask_b32_e64 v97, v173, v82, s[12:13]
	v_fma_f32 v98, v166, v98, -v129
	v_fma_f32 v82, v168, s77, v97
	v_fma_f32 v83, v168, s95, v97
	v_fma_f32 v84, v168, s4, v97
	v_fma_f32 v85, v168, s5, v97
	v_fma_f32 v86, v168, s86, v97
	v_fma_f32 v87, v168, s87, v97
	v_fma_f32 v88, v168, s84, v97
	v_fma_f32 v89, v168, s85, v97
	v_fma_f32 v90, v168, s88, v97
	v_fma_f32 v91, v168, s89, v97
	v_fma_f32 v92, v168, s90, v97
	v_fma_f32 v93, v168, s91, v97
	v_fma_f32 v94, v168, s72, v97
	v_fma_f32 v95, v168, s73, v97
	v_fma_f32 v96, v168, s74, v97
	v_fma_f32 v97, v168, s75, v97
	v_cndmask_b32_e64 v122, v173, v98, s[12:13]
	v_fma_f32 v98, v166, s77, v122
	v_fma_f32 v99, v166, s95, v122
	v_fma_f32 v100, v166, s4, v122
	v_fma_f32 v101, v166, s5, v122
	v_fma_f32 v102, v166, s86, v122
	v_fma_f32 v103, v166, s87, v122
	v_fma_f32 v104, v166, s84, v122
	v_fma_f32 v105, v166, s85, v122
	v_fma_f32 v106, v166, s88, v122
	v_fma_f32 v107, v166, s89, v122
	v_fma_f32 v108, v166, s90, v122
	v_fma_f32 v109, v166, s91, v122
	v_fma_f32 v156, v166, s72, v122
	v_fma_f32 v157, v166, s73, v122
	v_fma_f32 v158, v166, s74, v122
	v_fma_f32 v159, v166, s75, v122
	s_setprio 1
	s_waitcnt lgkmcnt(7)
	v_mfma_f32_16x16x32_bf16 v[82:85], v[110:113], v[6:9], v[82:85]
	v_mfma_f32_16x16x32_bf16 v[98:101], v[110:113], v[14:17], v[98:101]
	s_waitcnt lgkmcnt(5)
	v_mfma_f32_16x16x32_bf16 v[86:89], v[118:121], v[6:9], v[86:89]
	v_mfma_f32_16x16x32_bf16 v[102:105], v[118:121], v[14:17], v[102:105]
	s_waitcnt lgkmcnt(3)
	v_mfma_f32_16x16x32_bf16 v[118:121], v[140:143], v[6:9], v[90:93]
	v_mfma_f32_16x16x32_bf16 v[140:143], v[140:143], v[14:17], v[106:109]
	s_waitcnt lgkmcnt(1)
	v_mfma_f32_16x16x32_bf16 v[160:163], v[148:151], v[6:9], v[94:97]
	v_mfma_f32_16x16x32_bf16 v[148:151], v[148:151], v[14:17], v[156:159]
	v_mfma_f32_16x16x32_bf16 v[110:113], v[114:117], v[2:5], v[82:85]
	v_mfma_f32_16x16x32_bf16 v[94:97], v[114:117], v[10:13], v[98:101]
	v_mfma_f32_16x16x32_bf16 v[106:109], v[134:137], v[2:5], v[86:89]
	v_mfma_f32_16x16x32_bf16 v[90:93], v[134:137], v[10:13], v[102:105]
	v_mfma_f32_16x16x32_bf16 v[102:105], v[144:147], v[2:5], v[118:121]
	v_mfma_f32_16x16x32_bf16 v[86:89], v[144:147], v[10:13], v[140:143]
	s_waitcnt lgkmcnt(0)
	v_mfma_f32_16x16x32_bf16 v[98:101], v[152:155], v[2:5], v[160:163]
	v_mfma_f32_16x16x32_bf16 v[82:85], v[152:155], v[10:13], v[148:151]
	s_setprio 0
	v_max3_f32 v114, v110, s96, v111
	v_max3_f32 v114, v114, v112, v113
	v_max3_f32 v114, v114, v106, v107
	v_max3_f32 v114, v114, v108, v109
	v_max3_f32 v114, v114, v102, v103
	v_max3_f32 v114, v114, v104, v105
	v_max3_f32 v114, v114, v98, v99
	v_max3_f32 v115, v114, v100, v101
	v_max3_f32 v114, v115, v94, v95
	v_max3_f32 v114, v114, v96, v97
	v_max3_f32 v114, v114, v90, v91
	v_max3_f32 v114, v114, v92, v93
	v_max3_f32 v114, v114, v86, v87
	v_max3_f32 v114, v114, v88, v89
	v_max3_f32 v114, v114, v82, v83
	v_max3_f32 v114, v114, v84, v85
	s_mov_b32 s12, 0x41000000
	v_cmp_lt_f32_e32 vcc, s12, v114
	s_cbranch_vccnz .LBB0_1626
	v_cmp_lt_f32_e32 vcc, s94, v114
	s_cbranch_vccz .LBB0_1602

.LBB0_1614:
	s_or_b64 exec, exec, s[12:13]
	v_lshl_add_u64 v[74:75], s[14:15], 2, v[74:75]
	v_lshl_add_u64 v[74:75], v[74:75], 0, v[164:165]
	global_load_dwordx4 v[76:79], v[74:75], off offset:16 nt
	global_load_dwordx4 v[88:91], v[74:75], off nt
	global_load_dwordx4 v[80:83], v[74:75], off offset:272 nt
	global_load_dwordx4 v[84:87], v[74:75], off offset:256 nt
	s_and_b64 vcc, exec, s[8:9]
	s_cbranch_vccnz .LBB0_1619
	s_lshr_b32 s12, s29, 3
	s_and_b32 s12, s12, 0x1ffffffc
	v_add_u32_e32 v74, s12, v182
	ds_read_b32 v74, v74 offset:16
	s_and_b32 s12, s29, 31
	s_waitcnt lgkmcnt(0)
	v_lshrrev_b32_e32 v75, s29, v74
	v_bfe_u32 v74, v74, s12, 1
	v_and_b32_e32 v75, 1, v75
	v_cmp_ne_u32_e32 vcc, 0, v74
	v_cmp_eq_u32_e64 s[12:13], 1, v75
	s_cbranch_vccz .LBB0_1619
	v_lshl_add_u32 v74, s29, 6, v130
	v_cvt_f32_i32_e32 v74, v74
	v_fma_f32 v75, v168, v74, -v128
	v_cndmask_b32_e64 v75, v173, v75, s[12:13]
	v_fma_f32 v92, v168, s77, v75
	v_fma_f32 v93, v168, s95, v75
	v_fma_f32 v94, v168, s4, v75
	v_fma_f32 v95, v168, s5, v75
	v_fma_f32 v96, v168, s86, v75
	v_fma_f32 v97, v168, s87, v75
	v_fma_f32 v98, v168, s84, v75
	v_fma_f32 v99, v168, s85, v75
	v_fma_f32 v100, v168, s88, v75
	v_fma_f32 v101, v168, s89, v75
	v_fma_f32 v102, v168, s90, v75
	v_fma_f32 v103, v168, s91, v75
	v_fma_f32 v104, v168, s72, v75
	v_fma_f32 v105, v168, s73, v75
	v_fma_f32 v106, v168, s74, v75
	v_fma_f32 v107, v168, s75, v75
	v_add_u32_e32 v75, v131, v184
	ds_read_b128 v[120:123], v75
	ds_read_b128 v[134:137], v75 offset:64
	ds_read_b128 v[140:143], v75 offset:2560
	ds_read_b128 v[144:147], v75 offset:2624
	ds_read_b128 v[148:151], v75 offset:5120
	ds_read_b128 v[152:155], v75 offset:5184
	ds_read_b128 v[156:159], v75 offset:7680
	ds_read_b128 v[160:163], v75 offset:7744
	v_fma_f32 v74, v166, v74, -v129
	v_cndmask_b32_e64 v74, v173, v74, s[12:13]
	v_fma_f32 v108, v166, s77, v74
	v_fma_f32 v109, v166, s95, v74
	v_fma_f32 v110, v166, s4, v74
	v_fma_f32 v111, v166, s5, v74
	v_fma_f32 v112, v166, s86, v74
	v_fma_f32 v113, v166, s87, v74
	v_fma_f32 v114, v166, s84, v74
	v_fma_f32 v115, v166, s85, v74
	v_fma_f32 v116, v166, s88, v74
	v_fma_f32 v117, v166, s89, v74
	v_fma_f32 v118, v166, s90, v74
	v_fma_f32 v119, v166, s91, v74
	v_fma_f32 v186, v166, s72, v74
	v_fma_f32 v187, v166, s73, v74
	v_fma_f32 v188, v166, s74, v74
	v_fma_f32 v189, v166, s75, v74
	s_setprio 1
	s_waitcnt lgkmcnt(7)
	v_mfma_f32_16x16x32_bf16 v[92:95], v[120:123], v[6:9], v[92:95]
	v_mfma_f32_16x16x32_bf16 v[108:111], v[120:123], v[14:17], v[108:111]
	s_waitcnt lgkmcnt(5)
	v_mfma_f32_16x16x32_bf16 v[96:99], v[140:143], v[6:9], v[96:99]
	v_mfma_f32_16x16x32_bf16 v[112:115], v[140:143], v[14:17], v[112:115]
	s_waitcnt lgkmcnt(3)
	v_mfma_f32_16x16x32_bf16 v[140:143], v[148:151], v[6:9], v[100:103]
	v_mfma_f32_16x16x32_bf16 v[148:151], v[148:151], v[14:17], v[116:119]
	s_waitcnt lgkmcnt(1)
	v_mfma_f32_16x16x32_bf16 v[190:193], v[156:159], v[6:9], v[104:107]
	v_mfma_f32_16x16x32_bf16 v[156:159], v[156:159], v[14:17], v[186:189]
	v_mfma_f32_16x16x32_bf16 v[120:123], v[134:137], v[2:5], v[92:95]
	v_mfma_f32_16x16x32_bf16 v[104:107], v[134:137], v[10:13], v[108:111]
	v_mfma_f32_16x16x32_bf16 v[116:119], v[144:147], v[2:5], v[96:99]
	v_mfma_f32_16x16x32_bf16 v[100:103], v[144:147], v[10:13], v[112:115]
	v_mfma_f32_16x16x32_bf16 v[112:115], v[152:155], v[2:5], v[140:143]
	v_mfma_f32_16x16x32_bf16 v[96:99], v[152:155], v[10:13], v[148:151]
	s_waitcnt lgkmcnt(0)
	v_mfma_f32_16x16x32_bf16 v[108:111], v[160:163], v[2:5], v[190:193]
	v_mfma_f32_16x16x32_bf16 v[92:95], v[160:163], v[10:13], v[156:159]
	s_setprio 0
	v_max3_f32 v74, v120, s96, v121
	v_max3_f32 v74, v74, v122, v123
	v_max3_f32 v74, v74, v116, v117
	v_max3_f32 v74, v74, v118, v119
	v_max3_f32 v74, v74, v112, v113
	v_max3_f32 v74, v74, v114, v115
	v_max3_f32 v74, v74, v108, v109
	v_max3_f32 v75, v74, v110, v111
	v_max3_f32 v74, v75, v104, v105
	v_max3_f32 v74, v74, v106, v107
	v_max3_f32 v74, v74, v100, v101
	v_max3_f32 v74, v74, v102, v103
	v_max3_f32 v74, v74, v96, v97
	v_max3_f32 v74, v74, v98, v99
	v_max3_f32 v74, v74, v92, v93
	v_max3_f32 v74, v74, v94, v95
	s_mov_b32 s12, 0x41000000
	v_cmp_lt_f32_e32 vcc, s12, v74
	s_cbranch_vccnz .LBB0_1627
	v_cmp_lt_f32_e32 vcc, s94, v74
	s_cbranch_vccz .LBB0_1619

.LBB0_1638:
	s_or_b64 exec, exec, s[0:1]
	v_lshlrev_b64 v[18:19], 11, v[18:19]
	v_lshl_add_u64 v[18:19], v[20:21], 0, v[18:19]
	v_lshl_add_u64 v[18:19], s[14:15], 2, v[18:19]
	v_lshl_add_u64 v[22:23], v[18:19], 0, v[164:165]
	global_load_dwordx4 v[18:21], v[22:23], off nt
	global_load_dwordx4 v[24:27], v[22:23], off offset:16 nt
	global_load_dwordx4 v[28:31], v[22:23], off offset:256 nt
	global_load_dwordx4 v[32:35], v[22:23], off offset:272 nt
	v_min_i32_e32 v22, 0x47, v170
	v_cmp_lt_i32_e32 vcc, 63, v170
	s_waitcnt vmcnt(3)
	v_cvt_pk_bf16_f32 v18, v18, v19
	v_cvt_pk_bf16_f32 v19, v20, v21
	s_waitcnt vmcnt(2)
	v_cvt_pk_bf16_f32 v20, v24, v25
	v_cvt_pk_bf16_f32 v21, v26, v27
	s_waitcnt vmcnt(1)
	v_cvt_pk_bf16_f32 v24, v28, v29
	v_cvt_pk_bf16_f32 v25, v30, v31
	s_waitcnt vmcnt(0)
	v_cvt_pk_bf16_f32 v26, v32, v33
	v_cvt_pk_bf16_f32 v27, v34, v35
	ds_write_b128 v183, v[18:21]
	ds_write_b128 v183, v[24:27] offset:10240
	s_and_saveexec_b64 s[0:1], vcc
	s_xor_b64 s[0:1], exec, s[0:1]
	s_lshl_b64 s[12:13], s[6:7], 9
	v_add_u32_e32 v18, 0x1b8, v22
	v_mov_b32_e32 v19, v165
	v_lshl_add_u64 v[18:19], s[12:13], 0, v[18:19]
	s_or_saveexec_b64 s[0:1], s[0:1]
	v_mov_b64_e32 v[20:21], s[92:93]
	s_xor_b64 exec, exec, s[0:1]
	s_cbranch_execz .LBB0_1642
	s_lshl_b64 s[12:13], s[6:7], 20
	v_readlane_b32 s36, v241, 18
	v_readlane_b32 s37, v241, 19
	s_add_u32 s12, s36, s12
	v_add_u32_e32 v18, 0x1c0, v22
	s_addc_u32 s13, s37, s13
	v_ashrrev_i32_e32 v19, 31, v18
	v_mov_b64_e32 v[20:21], s[12:13]
	v_readlane_b32 s38, v241, 20
	v_readlane_b32 s39, v241, 21
	v_readlane_b32 s40, v241, 22
	v_readlane_b32 s41, v241, 23
	v_readlane_b32 s42, v241, 24
	v_readlane_b32 s43, v241, 25
	v_readlane_b32 s44, v241, 26
	v_readlane_b32 s45, v241, 27
	v_readlane_b32 s46, v241, 28
	v_readlane_b32 s47, v241, 29
	v_readlane_b32 s48, v241, 30
	v_readlane_b32 s49, v241, 31
	v_readlane_b32 s50, v241, 32
	v_readlane_b32 s51, v241, 33
.LBB0_1642:
	s_or_b64 exec, exec, s[0:1]
	v_lshlrev_b64 v[18:19], 11, v[18:19]
	v_lshl_add_u64 v[18:19], v[20:21], 0, v[18:19]
	v_lshl_add_u64 v[18:19], s[14:15], 2, v[18:19]
	v_lshl_add_u64 v[22:23], v[18:19], 0, v[164:165]
	global_load_dwordx4 v[26:29], v[22:23], off offset:16 nt
	global_load_dwordx4 v[30:33], v[22:23], off nt
	global_load_dwordx4 v[18:21], v[22:23], off offset:272 nt
	s_nop 0
	global_load_dwordx4 v[22:25], v[22:23], off offset:256 nt
	s_movk_i32 s0, 0x7f
	v_min_i32_e32 v38, 0x87, v170
	v_cmp_lt_i32_e32 vcc, s0, v170
	s_waitcnt lgkmcnt(0)
	s_barrier
	s_and_saveexec_b64 s[0:1], vcc
	s_xor_b64 s[0:1], exec, s[0:1]
	s_lshl_b64 s[12:13], s[6:7], 9
	v_add_u32_e32 v34, 0x178, v38
	v_mov_b32_e32 v35, v165
	v_lshl_add_u64 v[34:35], s[12:13], 0, v[34:35]
	s_or_saveexec_b64 s[0:1], s[0:1]
	v_mov_b64_e32 v[36:37], s[92:93]
	s_xor_b64 exec, exec, s[0:1]
	s_cbranch_execz .LBB0_1646
	s_lshl_b64 s[12:13], s[6:7], 20
	v_readlane_b32 s36, v241, 18
	v_readlane_b32 s37, v241, 19
	s_add_u32 s12, s36, s12
	v_add_u32_e32 v34, 0x180, v38
	s_addc_u32 s13, s37, s13
	v_ashrrev_i32_e32 v35, 31, v34
	v_mov_b64_e32 v[36:37], s[12:13]
	v_readlane_b32 s38, v241, 20
	v_readlane_b32 s39, v241, 21
	v_readlane_b32 s40, v241, 22
	v_readlane_b32 s41, v241, 23
	v_readlane_b32 s42, v241, 24
	v_readlane_b32 s43, v241, 25
	v_readlane_b32 s44, v241, 26
	v_readlane_b32 s45, v241, 27
	v_readlane_b32 s46, v241, 28
	v_readlane_b32 s47, v241, 29
	v_readlane_b32 s48, v241, 30
	v_readlane_b32 s49, v241, 31
	v_readlane_b32 s50, v241, 32
	v_readlane_b32 s51, v241, 33
.LBB0_1646:
	s_or_b64 exec, exec, s[0:1]
	v_lshlrev_b64 v[34:35], 11, v[34:35]
	v_lshl_add_u64 v[34:35], v[36:37], 0, v[34:35]
	v_lshl_add_u64 v[34:35], s[14:15], 2, v[34:35]
	v_lshl_add_u64 v[42:43], v[34:35], 0, v[164:165]
	global_load_dwordx4 v[38:41], v[42:43], off offset:16 nt
	global_load_dwordx4 v[46:49], v[42:43], off nt
	global_load_dwordx4 v[34:37], v[42:43], off offset:272 nt
	s_nop 0
	global_load_dwordx4 v[42:45], v[42:43], off offset:256 nt
	s_andn2_b64 vcc, exec, s[10:11]
	s_mov_b64 s[0:1], -1
	s_cbranch_vccnz .LBB0_1648
	v_lshlrev_b32_e32 v50, 2, v138
	v_and_b32_e32 v51, 48, v176
	s_mov_b64 s[0:1], 0

.LBB0_1656:
	s_movk_i32 s0, 0xffc0
	v_cmp_ne_u32_e64 s[0:1], s0, v190
	v_mov_b32_e32 v19, v165
	s_nop 0
	v_cndmask_b32_e64 v18, 0, v190, s[0:1]
	v_add_u32_e32 v22, v18, v170
	v_min_i32_e32 v18, 0x207, v22
	v_lshl_add_u64 v[20:21], s[10:11], 0, v[18:19]
	v_ashrrev_i32_e32 v19, 31, v18
	v_cmp_gt_i32_e32 vcc, s18, v22
	v_mov_b32_e32 v22, s3
	s_nop 0
	v_cndmask_b32_e32 v19, v21, v19, vcc
	v_cndmask_b32_e32 v18, v20, v18, vcc
	v_mov_b32_e32 v20, s93
	v_mov_b32_e32 v21, s6
	v_cndmask_b32_e32 v21, v20, v21, vcc
	v_mov_b32_e32 v20, s92
	v_cndmask_b32_e32 v20, v20, v22, vcc
	v_lshlrev_b64 v[18:19], 11, v[18:19]
	v_lshl_add_u64 v[18:19], v[20:21], 0, v[18:19]
	v_lshl_add_u64 v[18:19], s[14:15], 2, v[18:19]
	v_lshl_add_u64 v[18:19], v[18:19], 0, v[164:165]
	global_load_dwordx4 v[66:69], v[18:19], off offset:16 nt
	global_load_dwordx4 v[70:73], v[18:19], off nt
	global_load_dwordx4 v[58:61], v[18:19], off offset:272 nt
	global_load_dwordx4 v[62:65], v[18:19], off offset:256 nt
	s_and_b64 vcc, exec, s[8:9]
	s_cbranch_vccnz .LBB0_1661
	v_add_u32_e32 v138, v186, v184
	ds_read_b128 v[46:49], v138 offset:20480
	ds_read_b128 v[50:53], v138 offset:20544
	ds_read_b128 v[54:57], v138 offset:23040
	ds_read_b128 v[122:125], v138 offset:23104
	ds_read_b128 v[126:129], v138 offset:25600
	ds_read_b128 v[130:133], v138 offset:25664
	ds_read_b128 v[134:137], v138 offset:28160
	ds_read_b128 v[138:141], v138 offset:28224
	v_add_u32_e32 v18, v189, v190
	v_add_u32_e32 v18, 0xfffffe80, v18
	v_cvt_f32_i32_e32 v34, v18
	v_fma_f32 v33, v168, v34, -v194
	v_fma_f32 v145, v166, v34, -v195
	v_fma_f32 v18, v168, s77, v33
	v_fma_f32 v19, v168, s95, v33
	v_fma_f32 v20, v168, s4, v33
	v_fma_f32 v21, v168, s5, v33
	v_fma_f32 v22, v168, s86, v33
	v_fma_f32 v23, v168, s87, v33
	v_fma_f32 v24, v168, s84, v33
	v_fma_f32 v25, v168, s85, v33
	v_fma_f32 v26, v168, s88, v33
	v_fma_f32 v27, v168, s89, v33
	v_fma_f32 v28, v168, s90, v33
	v_fma_f32 v29, v168, s91, v33
	v_fma_f32 v30, v168, s72, v33
	v_fma_f32 v31, v168, s73, v33
	v_fma_f32 v32, v168, s74, v33
	v_fma_f32 v33, v168, s75, v33
	v_fma_f32 v34, v166, s77, v145
	v_fma_f32 v35, v166, s95, v145
	v_fma_f32 v36, v166, s4, v145
	v_fma_f32 v37, v166, s5, v145
	v_fma_f32 v38, v166, s86, v145
	v_fma_f32 v39, v166, s87, v145
	v_fma_f32 v40, v166, s84, v145
	v_fma_f32 v41, v166, s85, v145
	v_fma_f32 v42, v166, s88, v145
	v_fma_f32 v43, v166, s89, v145
	v_fma_f32 v44, v166, s90, v145
	v_fma_f32 v45, v166, s91, v145
	v_fma_f32 v142, v166, s72, v145
	v_fma_f32 v143, v166, s73, v145
	v_fma_f32 v144, v166, s74, v145
	v_fma_f32 v145, v166, s75, v145
	s_setprio 1
	s_waitcnt lgkmcnt(7)
	v_mfma_f32_16x16x32_bf16 v[18:21], v[46:49], v[6:9], v[18:21]
	v_mfma_f32_16x16x32_bf16 v[34:37], v[46:49], v[14:17], v[34:37]
	s_waitcnt lgkmcnt(5)
	v_mfma_f32_16x16x32_bf16 v[22:25], v[54:57], v[6:9], v[22:25]
	v_mfma_f32_16x16x32_bf16 v[38:41], v[54:57], v[14:17], v[38:41]
	s_waitcnt lgkmcnt(3)
	v_mfma_f32_16x16x32_bf16 v[54:57], v[126:129], v[6:9], v[26:29]
	v_mfma_f32_16x16x32_bf16 v[126:129], v[126:129], v[14:17], v[42:45]
	s_waitcnt lgkmcnt(1)
	v_mfma_f32_16x16x32_bf16 v[146:149], v[134:137], v[6:9], v[30:33]
	v_mfma_f32_16x16x32_bf16 v[134:137], v[134:137], v[14:17], v[142:145]
	v_mfma_f32_16x16x32_bf16 v[46:49], v[50:53], v[2:5], v[18:21]
	v_mfma_f32_16x16x32_bf16 v[30:33], v[50:53], v[10:13], v[34:37]
	v_mfma_f32_16x16x32_bf16 v[42:45], v[122:125], v[2:5], v[22:25]
	v_mfma_f32_16x16x32_bf16 v[26:29], v[122:125], v[10:13], v[38:41]
	v_mfma_f32_16x16x32_bf16 v[38:41], v[130:133], v[2:5], v[54:57]
	v_mfma_f32_16x16x32_bf16 v[22:25], v[130:133], v[10:13], v[126:129]
	s_waitcnt lgkmcnt(0)
	v_mfma_f32_16x16x32_bf16 v[34:37], v[138:141], v[2:5], v[146:149]
	v_mfma_f32_16x16x32_bf16 v[18:21], v[138:141], v[10:13], v[134:137]
	s_setprio 0
	v_max3_f32 v50, v46, s96, v47
	v_max3_f32 v50, v50, v48, v49
	v_max3_f32 v50, v50, v42, v43
	v_max3_f32 v50, v50, v44, v45
	v_max3_f32 v50, v50, v38, v39
	v_max3_f32 v50, v50, v40, v41
	v_max3_f32 v50, v50, v34, v35
	v_max3_f32 v51, v50, v36, v37
	v_max3_f32 v50, v51, v30, v31
	v_max3_f32 v50, v50, v32, v33
	v_max3_f32 v50, v50, v26, v27
	v_max3_f32 v50, v50, v28, v29
	v_max3_f32 v50, v50, v22, v23
	v_max3_f32 v50, v50, v24, v25
	v_max3_f32 v50, v50, v18, v19
	v_max3_f32 v50, v50, v20, v21
	s_mov_b32 s7, 0x41000000
	v_cmp_lt_f32_e32 vcc, s7, v50
	s_cbranch_vccnz .LBB0_1667
	v_mov_b32_e32 v192, v195
	v_mov_b32_e32 v193, v194
	v_cmp_lt_f32_e32 vcc, s94, v50
	s_cbranch_vccz .LBB0_1660

.LBB0_1662:
	v_mov_b64_e32 v[54:55], v[74:75]
	v_mov_b64_e32 v[50:51], v[94:95]
	v_mov_b64_e32 v[56:57], v[76:77]
	v_mov_b64_e32 v[52:53], v[96:97]
	s_andn2_b64 vcc, exec, s[0:1]
	s_mov_b64 s[0:1], -1
	ds_write_b128 v183, v[114:117]
	ds_write_b128 v183, v[118:121] offset:10240
	s_waitcnt lgkmcnt(0)
	s_barrier
	s_cbranch_vccnz .LBB0_1655
	v_min_u32_e32 v74, 3, v191
	v_lshlrev_b32_e32 v74, 6, v74
	v_sub_u32_e32 v78, v188, v74
	v_min_i32_e32 v74, 0x207, v78
	v_mov_b32_e32 v75, v165
	v_lshl_add_u64 v[76:77], s[10:11], 0, v[74:75]
	v_ashrrev_i32_e32 v75, 31, v74
	v_cmp_gt_i32_e32 vcc, s18, v78
	v_mov_b32_e32 v78, s3
	v_mov_b64_e32 v[112:113], v[20:21]
	v_cndmask_b32_e32 v75, v77, v75, vcc
	v_cndmask_b32_e32 v74, v76, v74, vcc
	v_mov_b32_e32 v76, s93
	v_mov_b32_e32 v77, s6
	v_cndmask_b32_e32 v77, v76, v77, vcc
	v_mov_b32_e32 v76, s92
	v_cndmask_b32_e32 v76, v76, v78, vcc
	v_lshlrev_b64 v[74:75], 11, v[74:75]
	v_lshl_add_u64 v[74:75], v[76:77], 0, v[74:75]
	v_lshl_add_u64 v[74:75], s[14:15], 2, v[74:75]
	v_lshl_add_u64 v[74:75], v[74:75], 0, v[164:165]
	global_load_dwordx4 v[116:119], v[74:75], off offset:16 nt
	global_load_dwordx4 v[128:131], v[74:75], off nt
	global_load_dwordx4 v[120:123], v[74:75], off offset:272 nt
	global_load_dwordx4 v[124:127], v[74:75], off offset:256 nt
	v_mov_b64_e32 v[92:93], v[36:37]
	v_mov_b64_e32 v[108:109], v[24:25]
	v_mov_b64_e32 v[88:89], v[40:41]
	v_mov_b64_e32 v[104:105], v[28:29]
	v_mov_b64_e32 v[84:85], v[44:45]
	v_mov_b64_e32 v[100:101], v[32:33]
	v_mov_b64_e32 v[80:81], v[48:49]
	v_mov_b64_e32 v[76:77], v[56:57]
	v_mov_b64_e32 v[96:97], v[52:53]
	s_and_b64 vcc, exec, s[8:9]
	v_mov_b64_e32 v[110:111], v[18:19]
	v_mov_b64_e32 v[90:91], v[34:35]
	v_mov_b64_e32 v[106:107], v[22:23]
	v_mov_b64_e32 v[86:87], v[38:39]
	v_mov_b64_e32 v[102:103], v[26:27]
	v_mov_b64_e32 v[82:83], v[42:43]
	v_mov_b64_e32 v[98:99], v[30:31]
	v_mov_b64_e32 v[78:79], v[46:47]
	v_mov_b32_e32 v194, v193
	v_mov_b32_e32 v195, v192
	v_mov_b64_e32 v[74:75], v[54:55]
	v_mov_b64_e32 v[94:95], v[50:51]
	s_cbranch_vccnz .LBB0_1654
	v_add_u32_e32 v115, v186, v184
	ds_read_b128 v[102:105], v115
	ds_read_b128 v[106:109], v115 offset:64
	ds_read_b128 v[110:113], v115 offset:2560
	ds_read_b128 v[132:135], v115 offset:2624
	ds_read_b128 v[136:139], v115 offset:5120
	ds_read_b128 v[148:151], v115 offset:5184
	ds_read_b128 v[140:143], v115 offset:7680
	ds_read_b128 v[194:197], v115 offset:7744
	v_add_u32_e32 v74, v189, v190
	v_add_u32_e32 v74, 0xfffffe40, v74
	v_cvt_f32_i32_e32 v90, v74
	v_fma_f32 v89, v168, v90, -v193
	v_fma_f32 v114, v166, v90, -v192
	v_fma_f32 v74, v168, s77, v89
	v_fma_f32 v75, v168, s95, v89
	v_fma_f32 v76, v168, s4, v89
	v_fma_f32 v77, v168, s5, v89
	v_fma_f32 v78, v168, s86, v89
	v_fma_f32 v79, v168, s87, v89
	v_fma_f32 v80, v168, s84, v89
	v_fma_f32 v81, v168, s85, v89
	v_fma_f32 v82, v168, s88, v89
	v_fma_f32 v83, v168, s89, v89
	v_fma_f32 v84, v168, s90, v89
	v_fma_f32 v85, v168, s91, v89
	v_fma_f32 v86, v168, s72, v89
	v_fma_f32 v87, v168, s73, v89
	v_fma_f32 v88, v168, s74, v89
	v_fma_f32 v89, v168, s75, v89
	v_fma_f32 v90, v166, s77, v114
	v_fma_f32 v91, v166, s95, v114
	v_fma_f32 v92, v166, s4, v114
	v_fma_f32 v93, v166, s5, v114
	v_fma_f32 v94, v166, s86, v114
	v_fma_f32 v95, v166, s87, v114
	v_fma_f32 v96, v166, s84, v114
	v_fma_f32 v97, v166, s85, v114
	v_fma_f32 v98, v166, s88, v114
	v_fma_f32 v99, v166, s89, v114
	v_fma_f32 v100, v166, s90, v114
	v_fma_f32 v101, v166, s91, v114
	v_fma_f32 v144, v166, s72, v114
	v_fma_f32 v145, v166, s73, v114
	v_fma_f32 v146, v166, s74, v114
	v_fma_f32 v147, v166, s75, v114
	s_setprio 1
	s_waitcnt lgkmcnt(7)
	v_mfma_f32_16x16x32_bf16 v[74:77], v[102:105], v[6:9], v[74:77]
	v_mfma_f32_16x16x32_bf16 v[90:93], v[102:105], v[14:17], v[90:93]
	s_waitcnt lgkmcnt(5)
	v_mfma_f32_16x16x32_bf16 v[78:81], v[110:113], v[6:9], v[78:81]
	v_mfma_f32_16x16x32_bf16 v[94:97], v[110:113], v[14:17], v[94:97]
	s_waitcnt lgkmcnt(3)
	v_mfma_f32_16x16x32_bf16 v[82:85], v[136:139], v[6:9], v[82:85]
	v_mfma_f32_16x16x32_bf16 v[98:101], v[136:139], v[14:17], v[98:101]
	s_waitcnt lgkmcnt(1)
	v_mfma_f32_16x16x32_bf16 v[86:89], v[140:143], v[6:9], v[86:89]
	v_mfma_f32_16x16x32_bf16 v[102:105], v[140:143], v[14:17], v[144:147]
	v_mfma_f32_16x16x32_bf16 v[160:163], v[106:109], v[2:5], v[74:77]
	v_mfma_f32_16x16x32_bf16 v[144:147], v[106:109], v[10:13], v[90:93]
	v_mfma_f32_16x16x32_bf16 v[156:159], v[132:135], v[2:5], v[78:81]
	v_mfma_f32_16x16x32_bf16 v[140:143], v[132:135], v[10:13], v[94:97]
	v_mfma_f32_16x16x32_bf16 v[152:155], v[148:151], v[2:5], v[82:85]
	v_mfma_f32_16x16x32_bf16 v[136:139], v[148:151], v[10:13], v[98:101]
	s_waitcnt lgkmcnt(0)
	v_mfma_f32_16x16x32_bf16 v[148:151], v[194:197], v[2:5], v[86:89]
	v_mfma_f32_16x16x32_bf16 v[132:135], v[194:197], v[10:13], v[102:105]
	s_setprio 0
	v_max3_f32 v74, v160, s96, v161
	v_max3_f32 v74, v74, v162, v163
	v_max3_f32 v74, v74, v156, v157
	v_max3_f32 v74, v74, v158, v159
	v_max3_f32 v74, v74, v152, v153
	v_max3_f32 v74, v74, v154, v155
	v_max3_f32 v74, v74, v148, v149
	v_max3_f32 v115, v74, v150, v151
	v_max3_f32 v74, v115, v144, v145
	v_max3_f32 v74, v74, v146, v147
	v_max3_f32 v74, v74, v140, v141
	v_max3_f32 v74, v74, v142, v143
	v_max3_f32 v74, v74, v136, v137
	v_max3_f32 v74, v74, v138, v139
	v_max3_f32 v74, v74, v132, v133
	v_max3_f32 v114, v74, v134, v135
	s_mov_b32 s0, 0x41000000
	v_mov_b64_e32 v[96:97], v[52:53]
	v_mov_b64_e32 v[76:77], v[56:57]
	v_mov_b64_e32 v[80:81], v[48:49]
	v_mov_b64_e32 v[100:101], v[32:33]
	v_mov_b64_e32 v[84:85], v[44:45]
	v_mov_b64_e32 v[104:105], v[28:29]
	v_mov_b64_e32 v[88:89], v[40:41]
	v_mov_b64_e32 v[108:109], v[24:25]
	v_mov_b64_e32 v[92:93], v[36:37]
	v_mov_b64_e32 v[112:113], v[20:21]
	v_cmp_lt_f32_e32 vcc, s0, v114
	v_mov_b64_e32 v[94:95], v[50:51]
	v_mov_b64_e32 v[74:75], v[54:55]
	v_mov_b32_e32 v195, v192
	v_mov_b32_e32 v194, v193
	v_mov_b64_e32 v[78:79], v[46:47]
	v_mov_b64_e32 v[98:99], v[30:31]
	v_mov_b64_e32 v[82:83], v[42:43]
	v_mov_b64_e32 v[102:103], v[26:27]
	v_mov_b64_e32 v[86:87], v[38:39]
	v_mov_b64_e32 v[106:107], v[22:23]
	v_mov_b64_e32 v[90:91], v[34:35]
	v_mov_b64_e32 v[110:111], v[18:19]
	s_cbranch_vccnz .LBB0_1668
	v_cmp_lt_f32_e32 vcc, s94, v114
	s_cbranch_vccz .LBB0_1654
